# s_setprio 1 issued before the load segment's counted waits so the opening barrier follows the waits directly
# baseline (speedup 1.0000x reference)
.LBB0_1516:
	v_add_u32_e32 v156, s83, v142
	v_add_u32_e32 v172, s44, v142
	s_add_u32 s8, s37, s6
	ds_read_b128 v[144:147], v156
	ds_read_b128 v[148:151], v156 offset:1024
	ds_read_b128 v[152:155], v156 offset:2048
	ds_read_b128 v[156:159], v156 offset:3072
	ds_read_b128 v[160:163], v172
	ds_read_b128 v[164:167], v172 offset:1024
	ds_read_b128 v[168:171], v172 offset:2048
	ds_read_b128 v[172:175], v172 offset:3072
	s_addc_u32 s9, s40, s7
	s_add_u32 s8, s8, 0x20400100
	s_addc_u32 s9, s9, 0
	s_add_u32 s46, s41, s6
	s_addc_u32 s47, s42, s7
	s_cmpk_eq_i32 s6, 0xf00
	s_cselect_b32 s11, s5, s9
	s_cselect_b32 s10, s4, s8
	s_cselect_b32 s9, s3, s47
	s_cselect_b32 s8, s2, s46
	v_lshl_add_u64 v[208:209], v[138:139], 0, s[6:7]
	s_add_i32 m0, s16, 0xc000
	ds_read_b128 v[176:179], v143
	ds_read_b128 v[180:183], v143 offset:1024
	ds_read_b128 v[184:187], v143 offset:2048
	ds_read_b128 v[188:191], v143 offset:3072
	ds_read_b128 v[192:195], v143 offset:4096
	ds_read_b128 v[196:199], v143 offset:5120
	ds_read_b128 v[200:203], v143 offset:6144
	ds_read_b128 v[204:207], v143 offset:7168
	global_load_lds_dwordx4 v[208:209], off
	v_lshl_add_u64 v[208:209], v[140:141], 0, s[6:7]
	s_add_i32 m0, s16, 0xe000
	s_nop 0
	global_load_lds_dwordx4 v[208:209], off
	s_setprio 1
	s_waitcnt vmcnt(8)
	s_waitcnt lgkmcnt(0)
	s_barrier
	s_cmp_lg_u32 s101, 0
	s_cbranch_scc1 .Lt13a_0
	v_mfma_f32_16x16x32_bf16 v[128:131], v[144:147], v[176:179], v[128:131]
	v_mfma_f32_16x16x32_bf16 v[128:131], v[148:151], v[180:183], v[128:131]
	v_mfma_f32_16x16x32_bf16 v[112:115], v[144:147], v[184:187], v[112:115]
	v_mfma_f32_16x16x32_bf16 v[112:115], v[148:151], v[188:191], v[112:115]
	v_mfma_f32_16x16x32_bf16 v[96:99], v[144:147], v[192:195], v[96:99]
	v_mfma_f32_16x16x32_bf16 v[96:99], v[148:151], v[196:199], v[96:99]
	v_mfma_f32_16x16x32_bf16 v[80:83], v[144:147], v[200:203], v[80:83]
	v_mfma_f32_16x16x32_bf16 v[80:83], v[148:151], v[204:207], v[80:83]
	v_mfma_f32_16x16x32_bf16 v[76:79], v[152:155], v[200:203], v[76:79]
	v_mfma_f32_16x16x32_bf16 v[76:79], v[156:159], v[204:207], v[76:79]
	v_mfma_f32_16x16x32_bf16 v[92:95], v[152:155], v[192:195], v[92:95]
	v_mfma_f32_16x16x32_bf16 v[92:95], v[156:159], v[196:199], v[92:95]
	v_mfma_f32_16x16x32_bf16 v[108:111], v[152:155], v[184:187], v[108:111]
	v_mfma_f32_16x16x32_bf16 v[108:111], v[156:159], v[188:191], v[108:111]
	v_mfma_f32_16x16x32_bf16 v[124:127], v[152:155], v[176:179], v[124:127]
	v_mfma_f32_16x16x32_bf16 v[124:127], v[156:159], v[180:183], v[124:127]

.Lt13b_0:
	s_barrier
	s_setprio 0
	s_mov_b32 m0, s13
	v_lshl_add_u64 v[208:209], s[8:9], 0, v[2:3]
	s_add_u32 s46, s8, 0x80000
	ds_read_b128 v[176:179], v143 offset:16384
	ds_read_b128 v[180:183], v143 offset:17408
	ds_read_b128 v[184:187], v143 offset:18432
	ds_read_b128 v[188:191], v143 offset:19456
	ds_read_b128 v[192:195], v143 offset:20480
	ds_read_b128 v[196:199], v143 offset:21504
	ds_read_b128 v[200:203], v143 offset:22528
	ds_read_b128 v[204:207], v143 offset:23552
	global_load_lds_dwordx4 v[208:209], off
	v_lshl_add_u64 v[210:211], s[8:9], 0, v[136:137]
	s_mov_b32 m0, s14
	s_addc_u32 s47, s9, 0
	global_load_lds_dwordx4 v[210:211], off
	v_lshl_add_u64 v[216:217], s[46:47], 0, v[2:3]
	s_mov_b32 m0, s15
	v_lshl_add_u64 v[218:219], s[10:11], 0, v[134:135]
	global_load_lds_dwordx4 v[216:217], off
	v_lshl_add_u64 v[216:217], s[46:47], 0, v[136:137]
	s_mov_b32 m0, s19
	s_nop 0
	global_load_lds_dwordx4 v[216:217], off
	v_lshl_add_u64 v[216:217], s[10:11], 0, v[132:133]
	s_mov_b32 m0, s16
	s_nop 0
	global_load_lds_dwordx4 v[216:217], off
	s_mov_b32 m0, s20
	s_nop 0
	global_load_lds_dwordx4 v[218:219], off
	s_setprio 1
	s_waitcnt vmcnt(8)
	s_waitcnt lgkmcnt(0)
	s_barrier
	s_cmp_lg_u32 s101, 0
	s_cbranch_scc1 .Lt13a_1
	v_mfma_f32_16x16x32_bf16 v[64:67], v[144:147], v[176:179], v[64:67]
	v_mfma_f32_16x16x32_bf16 v[64:67], v[148:151], v[180:183], v[64:67]
	v_mfma_f32_16x16x32_bf16 v[48:51], v[144:147], v[184:187], v[48:51]
	v_mfma_f32_16x16x32_bf16 v[48:51], v[148:151], v[188:191], v[48:51]
	v_mfma_f32_16x16x32_bf16 v[32:35], v[144:147], v[192:195], v[32:35]
	v_mfma_f32_16x16x32_bf16 v[32:35], v[148:151], v[196:199], v[32:35]
	v_mfma_f32_16x16x32_bf16 v[16:19], v[144:147], v[200:203], v[16:19]
	v_mfma_f32_16x16x32_bf16 v[16:19], v[148:151], v[204:207], v[16:19]
	v_mfma_f32_16x16x32_bf16 v[12:15], v[152:155], v[200:203], v[12:15]
	v_mfma_f32_16x16x32_bf16 v[12:15], v[156:159], v[204:207], v[12:15]
	v_mfma_f32_16x16x32_bf16 v[28:31], v[152:155], v[192:195], v[28:31]
	v_mfma_f32_16x16x32_bf16 v[28:31], v[156:159], v[196:199], v[28:31]
	v_mfma_f32_16x16x32_bf16 v[44:47], v[152:155], v[184:187], v[44:47]
	v_mfma_f32_16x16x32_bf16 v[44:47], v[156:159], v[188:191], v[44:47]
	v_mfma_f32_16x16x32_bf16 v[60:63], v[152:155], v[176:179], v[60:63]
	v_mfma_f32_16x16x32_bf16 v[60:63], v[156:159], v[180:183], v[60:63]

.Lt13b_1:
	s_barrier
	s_setprio 0
	v_add_u32_e32 v156, s45, v142
	v_add_u32_e32 v172, s74, v142
	ds_read_b128 v[144:147], v156
	ds_read_b128 v[148:151], v156 offset:1024
	ds_read_b128 v[152:155], v156 offset:2048
	ds_read_b128 v[156:159], v156 offset:3072
	ds_read_b128 v[160:163], v172
	ds_read_b128 v[164:167], v172 offset:1024
	ds_read_b128 v[168:171], v172 offset:2048
	ds_read_b128 v[172:175], v172 offset:3072
	s_add_u32 s10, s10, 0x80000
	s_addc_u32 s11, s11, 0
	s_mov_b32 m0, s22
	v_lshl_add_u64 v[220:221], s[10:11], 0, v[132:133]
	ds_read_b128 v[176:179], v143 offset:32768
	ds_read_b128 v[180:183], v143 offset:33792
	ds_read_b128 v[184:187], v143 offset:34816
	ds_read_b128 v[188:191], v143 offset:35840
	ds_read_b128 v[192:195], v143 offset:36864
	ds_read_b128 v[196:199], v143 offset:37888
	ds_read_b128 v[200:203], v143 offset:38912
	ds_read_b128 v[204:207], v143 offset:39936
	global_load_lds_dwordx4 v[220:221], off
	v_lshl_add_u64 v[220:221], s[10:11], 0, v[134:135]
	s_mov_b32 m0, s23
	s_nop 0
	global_load_lds_dwordx4 v[220:221], off
	s_setprio 1
	s_waitcnt vmcnt(8)
	s_waitcnt lgkmcnt(0)
	s_barrier
	s_cmp_lg_u32 s101, 0
	s_cbranch_scc1 .Lt13a_2
	v_mfma_f32_16x16x32_bf16 v[128:131], v[144:147], v[176:179], v[128:131]
	v_mfma_f32_16x16x32_bf16 v[128:131], v[148:151], v[180:183], v[128:131]
	v_mfma_f32_16x16x32_bf16 v[112:115], v[144:147], v[184:187], v[112:115]
	v_mfma_f32_16x16x32_bf16 v[112:115], v[148:151], v[188:191], v[112:115]
	v_mfma_f32_16x16x32_bf16 v[96:99], v[144:147], v[192:195], v[96:99]
	v_mfma_f32_16x16x32_bf16 v[96:99], v[148:151], v[196:199], v[96:99]
	v_mfma_f32_16x16x32_bf16 v[80:83], v[144:147], v[200:203], v[80:83]
	v_mfma_f32_16x16x32_bf16 v[80:83], v[148:151], v[204:207], v[80:83]
	v_mfma_f32_16x16x32_bf16 v[76:79], v[152:155], v[200:203], v[76:79]
	v_mfma_f32_16x16x32_bf16 v[76:79], v[156:159], v[204:207], v[76:79]
	v_mfma_f32_16x16x32_bf16 v[92:95], v[152:155], v[192:195], v[92:95]
	v_mfma_f32_16x16x32_bf16 v[92:95], v[156:159], v[196:199], v[92:95]
	v_mfma_f32_16x16x32_bf16 v[108:111], v[152:155], v[184:187], v[108:111]
	v_mfma_f32_16x16x32_bf16 v[108:111], v[156:159], v[188:191], v[108:111]
	v_mfma_f32_16x16x32_bf16 v[124:127], v[152:155], v[176:179], v[124:127]
	v_mfma_f32_16x16x32_bf16 v[124:127], v[156:159], v[180:183], v[124:127]

.Lt13b_2:
	s_barrier
	s_setprio 0
	s_mov_b32 m0, s24
	v_lshl_add_u64 v[208:209], v[208:209], 0, s[64:65]
	s_add_u32 s8, s8, 0x80080
	ds_read_b128 v[176:179], v143 offset:49152
	ds_read_b128 v[180:183], v143 offset:50176
	ds_read_b128 v[184:187], v143 offset:51200
	ds_read_b128 v[188:191], v143 offset:52224
	ds_read_b128 v[192:195], v143 offset:53248
	ds_read_b128 v[196:199], v143 offset:54272
	ds_read_b128 v[200:203], v143 offset:55296
	ds_read_b128 v[204:207], v143 offset:56320
	global_load_lds_dwordx4 v[208:209], off
	v_lshl_add_u64 v[208:209], v[210:211], 0, s[64:65]
	s_mov_b32 m0, s25
	s_addc_u32 s9, s9, 0
	global_load_lds_dwordx4 v[208:209], off
	v_lshl_add_u64 v[208:209], s[8:9], 0, v[2:3]
	s_mov_b32 m0, s34
	s_nop 0
	global_load_lds_dwordx4 v[208:209], off
	v_lshl_add_u64 v[208:209], s[8:9], 0, v[136:137]
	s_mov_b32 m0, s35
	s_nop 0
	global_load_lds_dwordx4 v[208:209], off
	v_lshl_add_u64 v[208:209], v[216:217], 0, s[64:65]
	s_mov_b32 m0, s26
	s_nop 0
	global_load_lds_dwordx4 v[208:209], off
	v_lshl_add_u64 v[208:209], v[218:219], 0, s[64:65]
	s_mov_b32 m0, s27
	s_nop 0
	global_load_lds_dwordx4 v[208:209], off
	s_setprio 1
	s_waitcnt vmcnt(8)
	s_waitcnt lgkmcnt(0)
	s_barrier
	s_cmp_lg_u32 s101, 0
	s_cbranch_scc1 .Lt13a_3
	v_mfma_f32_16x16x32_bf16 v[64:67], v[144:147], v[176:179], v[64:67]
	v_mfma_f32_16x16x32_bf16 v[64:67], v[148:151], v[180:183], v[64:67]
	v_mfma_f32_16x16x32_bf16 v[48:51], v[144:147], v[184:187], v[48:51]
	v_mfma_f32_16x16x32_bf16 v[48:51], v[148:151], v[188:191], v[48:51]
	v_mfma_f32_16x16x32_bf16 v[32:35], v[144:147], v[192:195], v[32:35]
	v_mfma_f32_16x16x32_bf16 v[32:35], v[148:151], v[196:199], v[32:35]
	v_mfma_f32_16x16x32_bf16 v[16:19], v[144:147], v[200:203], v[16:19]
	v_mfma_f32_16x16x32_bf16 v[16:19], v[148:151], v[204:207], v[16:19]
	v_mfma_f32_16x16x32_bf16 v[12:15], v[152:155], v[200:203], v[12:15]
	v_mfma_f32_16x16x32_bf16 v[12:15], v[156:159], v[204:207], v[12:15]
	v_mfma_f32_16x16x32_bf16 v[28:31], v[152:155], v[192:195], v[28:31]
	v_mfma_f32_16x16x32_bf16 v[28:31], v[156:159], v[196:199], v[28:31]
	v_mfma_f32_16x16x32_bf16 v[44:47], v[152:155], v[184:187], v[44:47]
	v_mfma_f32_16x16x32_bf16 v[44:47], v[156:159], v[188:191], v[44:47]
	v_mfma_f32_16x16x32_bf16 v[60:63], v[152:155], v[176:179], v[60:63]
	v_mfma_f32_16x16x32_bf16 v[60:63], v[156:159], v[180:183], v[60:63]

.LBB0_1876:
	v_add_u32_e32 v2, s83, v144
	ds_read_b128 v[146:149], v2
	ds_read_b128 v[150:153], v2 offset:1024
	ds_read_b128 v[154:157], v2 offset:2048
	ds_read_b128 v[158:161], v2 offset:3072
	v_add_u32_e32 v2, s44, v144
	ds_read_b128 v[162:165], v2
	ds_read_b128 v[166:169], v2 offset:1024
	ds_read_b128 v[170:173], v2 offset:2048
	ds_read_b128 v[174:177], v2 offset:3072
	s_add_i32 s70, s18, 2
	s_add_u32 s71, s42, 0x80
	s_addc_u32 s19, s43, 0
	s_cmp_eq_u32 s57, s18
	s_cselect_b32 s18, s34, s71
	s_cselect_b32 s19, s35, s19
	s_cselect_b32 s77, s25, s69
	s_cselect_b32 s76, s24, s68
	v_lshl_add_u64 v[210:211], s[42:43], 0, v[140:141]
	s_add_i32 m0, s23, 0xc000
	ds_read_b128 v[178:181], v145
	ds_read_b128 v[182:185], v145 offset:1024
	ds_read_b128 v[186:189], v145 offset:2048
	ds_read_b128 v[190:193], v145 offset:3072
	ds_read_b128 v[194:197], v145 offset:4096
	ds_read_b128 v[198:201], v145 offset:5120
	ds_read_b128 v[202:205], v145 offset:6144
	ds_read_b128 v[206:209], v145 offset:7168
	global_load_lds_dwordx4 v[210:211], off
	v_lshl_add_u64 v[210:211], s[42:43], 0, v[142:143]
	s_add_i32 m0, s23, 0xe000
	s_nop 0
	global_load_lds_dwordx4 v[210:211], off
	s_setprio 1
	s_waitcnt vmcnt(8)
	s_waitcnt lgkmcnt(0)
	s_barrier
	v_mfma_f32_16x16x32_bf16 v[120:123], v[146:149], v[178:181], v[120:123]
	v_mfma_f32_16x16x32_bf16 v[120:123], v[150:153], v[182:185], v[120:123]
	v_mfma_f32_16x16x32_bf16 v[112:115], v[146:149], v[186:189], v[112:115]
	v_mfma_f32_16x16x32_bf16 v[112:115], v[150:153], v[190:193], v[112:115]
	v_mfma_f32_16x16x32_bf16 v[96:99], v[146:149], v[194:197], v[96:99]
	v_mfma_f32_16x16x32_bf16 v[96:99], v[150:153], v[198:201], v[96:99]
	v_mfma_f32_16x16x32_bf16 v[80:83], v[146:149], v[202:205], v[80:83]
	v_mfma_f32_16x16x32_bf16 v[80:83], v[150:153], v[206:209], v[80:83]
	v_mfma_f32_16x16x32_bf16 v[76:79], v[154:157], v[202:205], v[76:79]
	v_mfma_f32_16x16x32_bf16 v[76:79], v[158:161], v[206:209], v[76:79]
	v_mfma_f32_16x16x32_bf16 v[92:95], v[154:157], v[194:197], v[92:95]
	v_mfma_f32_16x16x32_bf16 v[92:95], v[158:161], v[198:201], v[92:95]
	v_mfma_f32_16x16x32_bf16 v[108:111], v[154:157], v[186:189], v[108:111]
	v_mfma_f32_16x16x32_bf16 v[108:111], v[158:161], v[190:193], v[108:111]
	v_mfma_f32_16x16x32_bf16 v[128:131], v[154:157], v[178:181], v[128:131]
	v_mfma_f32_16x16x32_bf16 v[128:131], v[158:161], v[182:185], v[128:131]
	s_setprio 0
	s_setprio 1
	v_mfma_f32_16x16x32_bf16 v[124:127], v[162:165], v[178:181], v[124:127]
	v_mfma_f32_16x16x32_bf16 v[124:127], v[166:169], v[182:185], v[124:127]
	v_mfma_f32_16x16x32_bf16 v[104:107], v[162:165], v[186:189], v[104:107]
	v_mfma_f32_16x16x32_bf16 v[104:107], v[166:169], v[190:193], v[104:107]
	v_mfma_f32_16x16x32_bf16 v[88:91], v[162:165], v[194:197], v[88:91]
	v_mfma_f32_16x16x32_bf16 v[88:91], v[166:169], v[198:201], v[88:91]
	v_mfma_f32_16x16x32_bf16 v[72:75], v[162:165], v[202:205], v[72:75]
	v_mfma_f32_16x16x32_bf16 v[72:75], v[166:169], v[206:209], v[72:75]
	v_mfma_f32_16x16x32_bf16 v[68:71], v[170:173], v[202:205], v[68:71]
	v_mfma_f32_16x16x32_bf16 v[68:71], v[174:177], v[206:209], v[68:71]
	v_mfma_f32_16x16x32_bf16 v[84:87], v[170:173], v[194:197], v[84:87]
	v_mfma_f32_16x16x32_bf16 v[84:87], v[174:177], v[198:201], v[84:87]
	v_mfma_f32_16x16x32_bf16 v[100:103], v[170:173], v[186:189], v[100:103]
	v_mfma_f32_16x16x32_bf16 v[100:103], v[174:177], v[190:193], v[100:103]
	v_mfma_f32_16x16x32_bf16 v[116:119], v[170:173], v[178:181], v[116:119]
	v_mfma_f32_16x16x32_bf16 v[116:119], v[174:177], v[182:185], v[116:119]
	s_barrier
	s_setprio 0
	s_mov_b32 m0, s16
	v_lshl_add_u64 v[210:211], s[76:77], 0, v[134:135]
	v_lshl_add_u64 v[216:217], s[76:77], 0, v[138:139]
	s_add_u32 s76, s76, s4
	ds_read_b128 v[178:181], v145 offset:16384
	ds_read_b128 v[182:185], v145 offset:17408
	ds_read_b128 v[186:189], v145 offset:18432
	ds_read_b128 v[190:193], v145 offset:19456
	ds_read_b128 v[194:197], v145 offset:20480
	ds_read_b128 v[198:201], v145 offset:21504
	ds_read_b128 v[202:205], v145 offset:22528
	ds_read_b128 v[206:209], v145 offset:23552
	global_load_lds_dwordx4 v[210:211], off
	s_mov_b32 m0, s20
	s_addc_u32 s77, s77, s5
	global_load_lds_dwordx4 v[216:217], off
	v_lshl_add_u64 v[218:219], s[76:77], 0, v[134:135]
	s_mov_b32 m0, s21
	v_lshl_add_u64 v[220:221], s[76:77], 0, v[138:139]
	global_load_lds_dwordx4 v[218:219], off
	s_mov_b32 m0, s22
	v_lshl_add_u64 v[222:223], s[18:19], 0, v[132:133]
	global_load_lds_dwordx4 v[220:221], off
	s_mov_b32 m0, s23
	v_lshl_add_u64 v[224:225], s[18:19], 0, v[136:137]
	global_load_lds_dwordx4 v[222:223], off
	s_mov_b32 m0, s26
	s_nop 0
	global_load_lds_dwordx4 v[224:225], off
	s_setprio 1
	s_waitcnt vmcnt(8)
	s_waitcnt lgkmcnt(0)
	s_barrier
	v_mfma_f32_16x16x32_bf16 v[64:67], v[146:149], v[178:181], v[64:67]
	v_mfma_f32_16x16x32_bf16 v[64:67], v[150:153], v[182:185], v[64:67]
	v_mfma_f32_16x16x32_bf16 v[48:51], v[146:149], v[186:189], v[48:51]
	v_mfma_f32_16x16x32_bf16 v[48:51], v[150:153], v[190:193], v[48:51]
	v_mfma_f32_16x16x32_bf16 v[32:35], v[146:149], v[194:197], v[32:35]
	v_mfma_f32_16x16x32_bf16 v[32:35], v[150:153], v[198:201], v[32:35]
	v_mfma_f32_16x16x32_bf16 v[16:19], v[146:149], v[202:205], v[16:19]
	v_mfma_f32_16x16x32_bf16 v[16:19], v[150:153], v[206:209], v[16:19]
	v_mfma_f32_16x16x32_bf16 v[12:15], v[154:157], v[202:205], v[12:15]
	v_mfma_f32_16x16x32_bf16 v[12:15], v[158:161], v[206:209], v[12:15]
	v_mfma_f32_16x16x32_bf16 v[28:31], v[154:157], v[194:197], v[28:31]
	v_mfma_f32_16x16x32_bf16 v[28:31], v[158:161], v[198:201], v[28:31]
	v_mfma_f32_16x16x32_bf16 v[44:47], v[154:157], v[186:189], v[44:47]
	v_mfma_f32_16x16x32_bf16 v[44:47], v[158:161], v[190:193], v[44:47]
	v_mfma_f32_16x16x32_bf16 v[60:63], v[154:157], v[178:181], v[60:63]
	v_mfma_f32_16x16x32_bf16 v[60:63], v[158:161], v[182:185], v[60:63]
	s_setprio 0
	s_setprio 1
	v_mfma_f32_16x16x32_bf16 v[56:59], v[162:165], v[178:181], v[56:59]
	v_mfma_f32_16x16x32_bf16 v[56:59], v[166:169], v[182:185], v[56:59]
	v_mfma_f32_16x16x32_bf16 v[40:43], v[162:165], v[186:189], v[40:43]
	v_mfma_f32_16x16x32_bf16 v[40:43], v[166:169], v[190:193], v[40:43]
	v_mfma_f32_16x16x32_bf16 v[24:27], v[162:165], v[194:197], v[24:27]
	v_mfma_f32_16x16x32_bf16 v[24:27], v[166:169], v[198:201], v[24:27]
	v_mfma_f32_16x16x32_bf16 v[8:11], v[162:165], v[202:205], v[8:11]
	v_mfma_f32_16x16x32_bf16 v[8:11], v[166:169], v[206:209], v[8:11]
	v_mfma_f32_16x16x32_bf16 v[4:7], v[170:173], v[202:205], v[4:7]
	v_mfma_f32_16x16x32_bf16 v[4:7], v[174:177], v[206:209], v[4:7]
	v_mfma_f32_16x16x32_bf16 v[20:23], v[170:173], v[194:197], v[20:23]
	v_mfma_f32_16x16x32_bf16 v[20:23], v[174:177], v[198:201], v[20:23]
	v_mfma_f32_16x16x32_bf16 v[36:39], v[170:173], v[186:189], v[36:39]
	v_mfma_f32_16x16x32_bf16 v[36:39], v[174:177], v[190:193], v[36:39]
	v_mfma_f32_16x16x32_bf16 v[52:55], v[170:173], v[178:181], v[52:55]
	v_mfma_f32_16x16x32_bf16 v[52:55], v[174:177], v[182:185], v[52:55]
	s_barrier
	s_setprio 0
	v_add_u32_e32 v2, s45, v144
	ds_read_b128 v[146:149], v2
	ds_read_b128 v[150:153], v2 offset:1024
	ds_read_b128 v[154:157], v2 offset:2048
	ds_read_b128 v[158:161], v2 offset:3072
	v_add_u32_e32 v2, s74, v144
	ds_read_b128 v[162:165], v2
	ds_read_b128 v[166:169], v2 offset:1024
	ds_read_b128 v[170:173], v2 offset:2048
	ds_read_b128 v[174:177], v2 offset:3072
	s_add_u32 s18, s18, s4
	s_addc_u32 s19, s19, s5
	s_mov_b32 m0, s27
	v_lshl_add_u64 v[226:227], s[18:19], 0, v[132:133]
	ds_read_b128 v[178:181], v145 offset:32768
	ds_read_b128 v[182:185], v145 offset:33792
	ds_read_b128 v[186:189], v145 offset:34816
	ds_read_b128 v[190:193], v145 offset:35840
	ds_read_b128 v[194:197], v145 offset:36864
	ds_read_b128 v[198:201], v145 offset:37888
	ds_read_b128 v[202:205], v145 offset:38912
	ds_read_b128 v[206:209], v145 offset:39936
	global_load_lds_dwordx4 v[226:227], off
	v_lshl_add_u64 v[226:227], s[18:19], 0, v[136:137]
	s_mov_b32 m0, s37
	s_nop 0
	global_load_lds_dwordx4 v[226:227], off
	s_setprio 1
	s_waitcnt vmcnt(8)
	s_waitcnt lgkmcnt(0)
	s_barrier
	v_mfma_f32_16x16x32_bf16 v[120:123], v[146:149], v[178:181], v[120:123]
	v_mfma_f32_16x16x32_bf16 v[120:123], v[150:153], v[182:185], v[120:123]
	v_mfma_f32_16x16x32_bf16 v[112:115], v[146:149], v[186:189], v[112:115]
	v_mfma_f32_16x16x32_bf16 v[112:115], v[150:153], v[190:193], v[112:115]
	v_mfma_f32_16x16x32_bf16 v[96:99], v[146:149], v[194:197], v[96:99]
	v_mfma_f32_16x16x32_bf16 v[96:99], v[150:153], v[198:201], v[96:99]
	v_mfma_f32_16x16x32_bf16 v[80:83], v[146:149], v[202:205], v[80:83]
	v_mfma_f32_16x16x32_bf16 v[80:83], v[150:153], v[206:209], v[80:83]
	v_mfma_f32_16x16x32_bf16 v[76:79], v[154:157], v[202:205], v[76:79]
	v_mfma_f32_16x16x32_bf16 v[76:79], v[158:161], v[206:209], v[76:79]
	v_mfma_f32_16x16x32_bf16 v[92:95], v[154:157], v[194:197], v[92:95]
	v_mfma_f32_16x16x32_bf16 v[92:95], v[158:161], v[198:201], v[92:95]
	v_mfma_f32_16x16x32_bf16 v[108:111], v[154:157], v[186:189], v[108:111]
	v_mfma_f32_16x16x32_bf16 v[108:111], v[158:161], v[190:193], v[108:111]
	v_mfma_f32_16x16x32_bf16 v[128:131], v[154:157], v[178:181], v[128:131]
	v_mfma_f32_16x16x32_bf16 v[128:131], v[158:161], v[182:185], v[128:131]
	s_setprio 0
	s_setprio 1
	v_mfma_f32_16x16x32_bf16 v[124:127], v[162:165], v[178:181], v[124:127]
	v_mfma_f32_16x16x32_bf16 v[124:127], v[166:169], v[182:185], v[124:127]
	v_mfma_f32_16x16x32_bf16 v[104:107], v[162:165], v[186:189], v[104:107]
	v_mfma_f32_16x16x32_bf16 v[104:107], v[166:169], v[190:193], v[104:107]
	v_mfma_f32_16x16x32_bf16 v[88:91], v[162:165], v[194:197], v[88:91]
	v_mfma_f32_16x16x32_bf16 v[88:91], v[166:169], v[198:201], v[88:91]
	v_mfma_f32_16x16x32_bf16 v[72:75], v[162:165], v[202:205], v[72:75]
	v_mfma_f32_16x16x32_bf16 v[72:75], v[166:169], v[206:209], v[72:75]
	v_mfma_f32_16x16x32_bf16 v[68:71], v[170:173], v[202:205], v[68:71]
	v_mfma_f32_16x16x32_bf16 v[68:71], v[174:177], v[206:209], v[68:71]
	v_mfma_f32_16x16x32_bf16 v[84:87], v[170:173], v[194:197], v[84:87]
	v_mfma_f32_16x16x32_bf16 v[84:87], v[174:177], v[198:201], v[84:87]
	v_mfma_f32_16x16x32_bf16 v[100:103], v[170:173], v[186:189], v[100:103]
	v_mfma_f32_16x16x32_bf16 v[100:103], v[174:177], v[190:193], v[100:103]
	v_mfma_f32_16x16x32_bf16 v[116:119], v[170:173], v[178:181], v[116:119]
	v_mfma_f32_16x16x32_bf16 v[116:119], v[174:177], v[182:185], v[116:119]
	s_barrier
	s_setprio 0
	s_mov_b32 m0, s49
	v_lshl_add_u64 v[210:211], v[210:211], 0, s[64:65]
	ds_read_b128 v[178:181], v145 offset:49152
	ds_read_b128 v[182:185], v145 offset:50176
	ds_read_b128 v[186:189], v145 offset:51200
	ds_read_b128 v[190:193], v145 offset:52224
	ds_read_b128 v[194:197], v145 offset:53248
	ds_read_b128 v[198:201], v145 offset:54272
	ds_read_b128 v[202:205], v145 offset:55296
	ds_read_b128 v[206:209], v145 offset:56320
	global_load_lds_dwordx4 v[210:211], off
	v_lshl_add_u64 v[210:211], v[216:217], 0, s[64:65]
	s_mov_b32 m0, s50
	s_nop 0
	global_load_lds_dwordx4 v[210:211], off
	v_lshl_add_u64 v[210:211], v[218:219], 0, s[64:65]
	s_mov_b32 m0, s53
	s_nop 0
	global_load_lds_dwordx4 v[210:211], off
	v_lshl_add_u64 v[210:211], v[220:221], 0, s[64:65]
	s_mov_b32 m0, s56
	s_nop 0
	global_load_lds_dwordx4 v[210:211], off
	v_lshl_add_u64 v[210:211], v[222:223], 0, s[64:65]
	s_mov_b32 m0, s51
	s_nop 0
	global_load_lds_dwordx4 v[210:211], off
	v_lshl_add_u64 v[210:211], v[224:225], 0, s[64:65]
	s_mov_b32 m0, s52
	s_nop 0
	global_load_lds_dwordx4 v[210:211], off
	s_setprio 1
	s_waitcnt vmcnt(8)
	s_waitcnt lgkmcnt(0)
	s_barrier
	v_mfma_f32_16x16x32_bf16 v[64:67], v[146:149], v[178:181], v[64:67]
	v_mfma_f32_16x16x32_bf16 v[64:67], v[150:153], v[182:185], v[64:67]
	v_mfma_f32_16x16x32_bf16 v[48:51], v[146:149], v[186:189], v[48:51]
	v_mfma_f32_16x16x32_bf16 v[48:51], v[150:153], v[190:193], v[48:51]
	v_mfma_f32_16x16x32_bf16 v[32:35], v[146:149], v[194:197], v[32:35]
	v_mfma_f32_16x16x32_bf16 v[32:35], v[150:153], v[198:201], v[32:35]
	v_mfma_f32_16x16x32_bf16 v[16:19], v[146:149], v[202:205], v[16:19]
	v_mfma_f32_16x16x32_bf16 v[16:19], v[150:153], v[206:209], v[16:19]
	v_mfma_f32_16x16x32_bf16 v[12:15], v[154:157], v[202:205], v[12:15]
	v_mfma_f32_16x16x32_bf16 v[12:15], v[158:161], v[206:209], v[12:15]
	v_mfma_f32_16x16x32_bf16 v[28:31], v[154:157], v[194:197], v[28:31]
	v_mfma_f32_16x16x32_bf16 v[28:31], v[158:161], v[198:201], v[28:31]
	v_mfma_f32_16x16x32_bf16 v[44:47], v[154:157], v[186:189], v[44:47]
	v_mfma_f32_16x16x32_bf16 v[44:47], v[158:161], v[190:193], v[44:47]
	v_mfma_f32_16x16x32_bf16 v[60:63], v[154:157], v[178:181], v[60:63]
	v_mfma_f32_16x16x32_bf16 v[60:63], v[158:161], v[182:185], v[60:63]
	s_setprio 0
	s_setprio 1
	v_mfma_f32_16x16x32_bf16 v[56:59], v[162:165], v[178:181], v[56:59]
	v_mfma_f32_16x16x32_bf16 v[56:59], v[166:169], v[182:185], v[56:59]
	v_mfma_f32_16x16x32_bf16 v[40:43], v[162:165], v[186:189], v[40:43]
	v_mfma_f32_16x16x32_bf16 v[40:43], v[166:169], v[190:193], v[40:43]
	v_mfma_f32_16x16x32_bf16 v[24:27], v[162:165], v[194:197], v[24:27]
	v_mfma_f32_16x16x32_bf16 v[24:27], v[166:169], v[198:201], v[24:27]
	v_mfma_f32_16x16x32_bf16 v[8:11], v[162:165], v[202:205], v[8:11]
	v_mfma_f32_16x16x32_bf16 v[8:11], v[166:169], v[206:209], v[8:11]
	v_mfma_f32_16x16x32_bf16 v[4:7], v[170:173], v[202:205], v[4:7]
	v_mfma_f32_16x16x32_bf16 v[4:7], v[174:177], v[206:209], v[4:7]
	v_mfma_f32_16x16x32_bf16 v[20:23], v[170:173], v[194:197], v[20:23]
	v_mfma_f32_16x16x32_bf16 v[20:23], v[174:177], v[198:201], v[20:23]
	v_mfma_f32_16x16x32_bf16 v[36:39], v[170:173], v[186:189], v[36:39]
	v_mfma_f32_16x16x32_bf16 v[36:39], v[174:177], v[190:193], v[36:39]
	v_mfma_f32_16x16x32_bf16 v[52:55], v[170:173], v[178:181], v[52:55]
	v_mfma_f32_16x16x32_bf16 v[52:55], v[174:177], v[182:185], v[52:55]
	s_barrier
	s_setprio 0
	s_add_u32 s42, s42, 0x100
	s_addc_u32 s43, s43, 0
	s_add_u32 s68, s68, 0x100
	s_addc_u32 s69, s69, 0
	s_cmp_ge_i32 s70, s46
	s_mov_b32 s18, s70
	s_cbranch_scc0 .LBB0_1876

.LBB0_1891:
	v_add_u32_e32 v2, s83, v189
	ds_read_b128 v[28:31], v2
	ds_read_b128 v[32:35], v2 offset:16
	ds_read_b128 v[20:23], v2 offset:2048
	ds_read_b128 v[24:27], v2 offset:2064
	v_add_u32_e32 v2, s44, v189
	ds_read_b128 v[12:15], v2
	ds_read_b128 v[16:19], v2 offset:16
	ds_read_b128 v[4:7], v2 offset:2048
	ds_read_b128 v[8:11], v2 offset:2064
	s_add_u32 s10, s8, 0xfffc0080
	s_addc_u32 s11, s9, -1
	s_cmp_eq_u32 s25, 12
	s_cselect_b32 s13, s3, s11
	s_cselect_b32 s12, s14, s10
	s_cselect_b32 s11, s15, s24
	s_cselect_b32 s10, s18, s19
	v_lshl_add_u64 v[208:209], s[8:9], 0, v[172:173]
	s_add_i32 m0, s16, 0xc000
	ds_read_b128 v[176:179], v191
	ds_read_b128 v[180:183], v191 offset:16
	ds_read_b128 v[192:195], v191 offset:2048
	ds_read_b128 v[196:199], v191 offset:2064
	ds_read_b128 v[200:203], v191 offset:4096
	ds_read_b128 v[204:207], v191 offset:4112
	ds_read_b128 v[216:219], v191 offset:6144
	ds_read_b128 v[220:223], v191 offset:6160
	global_load_lds_dwordx4 v[208:209], off
	v_lshl_add_u64 v[208:209], s[8:9], 0, v[174:175]
	s_add_i32 m0, s16, 0xe000
	s_nop 0
	global_load_lds_dwordx4 v[208:209], off
	s_setprio 1
	s_waitcnt vmcnt(8)
	s_waitcnt lgkmcnt(0)
	s_barrier
	v_mfma_scale_f32_16x16x128_f8f6f4 v[160:163], v[28:35], v[176:183], v[160:163], v187, v185 op_sel_hi:[0,0,0]
	v_mfma_scale_f32_16x16x128_f8f6f4 v[156:159], v[20:27], v[176:183], v[156:159], v187, v185 op_sel_hi:[0,0,0]
	v_mfma_scale_f32_16x16x128_f8f6f4 v[144:147], v[28:35], v[192:199], v[144:147], v187, v185 op_sel_hi:[0,0,0]
	v_mfma_scale_f32_16x16x128_f8f6f4 v[140:143], v[20:27], v[192:199], v[140:143], v187, v185 op_sel_hi:[0,0,0]
	v_mfma_scale_f32_16x16x128_f8f6f4 v[128:131], v[28:35], v[200:207], v[128:131], v187, v185 op_sel_hi:[0,0,0]
	v_mfma_scale_f32_16x16x128_f8f6f4 v[124:127], v[20:27], v[200:207], v[124:127], v187, v185 op_sel_hi:[0,0,0]
	v_mfma_scale_f32_16x16x128_f8f6f4 v[112:115], v[28:35], v[216:223], v[112:115], v187, v185 op_sel_hi:[0,0,0]
	v_mfma_scale_f32_16x16x128_f8f6f4 v[108:111], v[20:27], v[216:223], v[108:111], v187, v185 op_sel_hi:[0,0,0]
	s_setprio 0
	s_setprio 1
	v_mfma_scale_f32_16x16x128_f8f6f4 v[152:155], v[12:19], v[176:183], v[152:155], v187, v185 op_sel_hi:[0,0,0]
	v_mfma_scale_f32_16x16x128_f8f6f4 v[148:151], v[4:11], v[176:183], v[148:151], v187, v185 op_sel_hi:[0,0,0]
	v_mfma_scale_f32_16x16x128_f8f6f4 v[136:139], v[12:19], v[192:199], v[136:139], v187, v185 op_sel_hi:[0,0,0]
	v_mfma_scale_f32_16x16x128_f8f6f4 v[132:135], v[4:11], v[192:199], v[132:135], v187, v185 op_sel_hi:[0,0,0]
	v_mfma_scale_f32_16x16x128_f8f6f4 v[120:123], v[12:19], v[200:207], v[120:123], v187, v185 op_sel_hi:[0,0,0]
	v_mfma_scale_f32_16x16x128_f8f6f4 v[116:119], v[4:11], v[200:207], v[116:119], v187, v185 op_sel_hi:[0,0,0]
	v_mfma_scale_f32_16x16x128_f8f6f4 v[104:107], v[12:19], v[216:223], v[104:107], v187, v185 op_sel_hi:[0,0,0]
	v_mfma_scale_f32_16x16x128_f8f6f4 v[100:103], v[4:11], v[216:223], v[100:103], v187, v185 op_sel_hi:[0,0,0]
	s_barrier
	s_setprio 0
	s_mov_b32 m0, s22
	v_lshl_add_u64 v[176:177], s[10:11], 0, v[166:167]
	s_add_u32 s56, s10, 0x40000
	ds_read_b128 v[192:195], v191 offset:16384
	ds_read_b128 v[196:199], v191 offset:16400
	ds_read_b128 v[200:203], v191 offset:18432
	ds_read_b128 v[204:207], v191 offset:18448
	ds_read_b128 v[216:219], v191 offset:20480
	ds_read_b128 v[220:223], v191 offset:20496
	ds_read_b128 v[224:227], v191 offset:22528
	ds_read_b128 v[228:231], v191 offset:22544
	global_load_lds_dwordx4 v[176:177], off
	v_lshl_add_u64 v[178:179], s[10:11], 0, v[170:171]
	s_mov_b32 m0, s23
	s_addc_u32 s57, s11, 0
	global_load_lds_dwordx4 v[178:179], off
	v_lshl_add_u64 v[180:181], s[56:57], 0, v[166:167]
	s_mov_b32 m0, s75
	v_lshl_add_u64 v[182:183], s[12:13], 0, v[168:169]
	global_load_lds_dwordx4 v[180:181], off
	v_lshl_add_u64 v[180:181], s[56:57], 0, v[170:171]
	s_mov_b32 m0, s37
	s_nop 0
	global_load_lds_dwordx4 v[180:181], off
	v_lshl_add_u64 v[180:181], s[12:13], 0, v[164:165]
	s_mov_b32 m0, s16
	s_nop 0
	global_load_lds_dwordx4 v[180:181], off
	s_mov_b32 m0, s73
	s_nop 0
	global_load_lds_dwordx4 v[182:183], off
	s_setprio 1
	s_waitcnt vmcnt(8)
	s_waitcnt lgkmcnt(0)
	s_barrier
	v_mfma_scale_f32_16x16x128_f8f6f4 v[96:99], v[28:35], v[192:199], v[96:99], v187, v185 op_sel_hi:[0,0,0]
	v_mfma_scale_f32_16x16x128_f8f6f4 v[92:95], v[20:27], v[192:199], v[92:95], v187, v185 op_sel_hi:[0,0,0]
	v_mfma_scale_f32_16x16x128_f8f6f4 v[80:83], v[28:35], v[200:207], v[80:83], v187, v185 op_sel_hi:[0,0,0]
	v_mfma_scale_f32_16x16x128_f8f6f4 v[76:79], v[20:27], v[200:207], v[76:79], v187, v185 op_sel_hi:[0,0,0]
	v_mfma_scale_f32_16x16x128_f8f6f4 v[64:67], v[28:35], v[216:223], v[64:67], v187, v185 op_sel_hi:[0,0,0]
	v_mfma_scale_f32_16x16x128_f8f6f4 v[60:63], v[20:27], v[216:223], v[60:63], v187, v185 op_sel_hi:[0,0,0]
	v_mfma_scale_f32_16x16x128_f8f6f4 v[48:51], v[28:35], v[224:231], v[48:51], v187, v185 op_sel_hi:[0,0,0]
	v_mfma_scale_f32_16x16x128_f8f6f4 v[44:47], v[20:27], v[224:231], v[44:47], v187, v185 op_sel_hi:[0,0,0]
	s_setprio 0
	s_setprio 1
	v_mfma_scale_f32_16x16x128_f8f6f4 v[88:91], v[12:19], v[192:199], v[88:91], v187, v185 op_sel_hi:[0,0,0]
	v_mfma_scale_f32_16x16x128_f8f6f4 v[84:87], v[4:11], v[192:199], v[84:87], v187, v185 op_sel_hi:[0,0,0]
	v_mfma_scale_f32_16x16x128_f8f6f4 v[72:75], v[12:19], v[200:207], v[72:75], v187, v185 op_sel_hi:[0,0,0]
	v_mfma_scale_f32_16x16x128_f8f6f4 v[68:71], v[4:11], v[200:207], v[68:71], v187, v185 op_sel_hi:[0,0,0]
	v_mfma_scale_f32_16x16x128_f8f6f4 v[56:59], v[12:19], v[216:223], v[56:59], v187, v185 op_sel_hi:[0,0,0]
	v_mfma_scale_f32_16x16x128_f8f6f4 v[52:55], v[4:11], v[216:223], v[52:55], v187, v185 op_sel_hi:[0,0,0]
	v_mfma_scale_f32_16x16x128_f8f6f4 v[40:43], v[12:19], v[224:231], v[40:43], v187, v185 op_sel_hi:[0,0,0]
	v_mfma_scale_f32_16x16x128_f8f6f4 v[36:39], v[4:11], v[224:231], v[36:39], v187, v185 op_sel_hi:[0,0,0]
	s_barrier
	s_setprio 0
	v_add_u32_e32 v2, s45, v189
	ds_read_b128 v[28:31], v2
	ds_read_b128 v[32:35], v2 offset:16
	ds_read_b128 v[20:23], v2 offset:2048
	ds_read_b128 v[24:27], v2 offset:2064
	v_add_u32_e32 v2, s74, v189
	ds_read_b128 v[12:15], v2
	ds_read_b128 v[16:19], v2 offset:16
	ds_read_b128 v[4:7], v2 offset:2048
	ds_read_b128 v[8:11], v2 offset:2064
	s_add_u32 s12, s12, 0x40000
	s_addc_u32 s13, s13, 0
	s_mov_b32 m0, s82
	v_lshl_add_u64 v[208:209], s[12:13], 0, v[164:165]
	ds_read_b128 v[192:195], v191 offset:32768
	ds_read_b128 v[196:199], v191 offset:32784
	ds_read_b128 v[200:203], v191 offset:34816
	ds_read_b128 v[204:207], v191 offset:34832
	ds_read_b128 v[216:219], v191 offset:36864
	ds_read_b128 v[220:223], v191 offset:36880
	ds_read_b128 v[224:227], v191 offset:38912
	ds_read_b128 v[228:231], v191 offset:38928
	global_load_lds_dwordx4 v[208:209], off
	v_lshl_add_u64 v[208:209], s[12:13], 0, v[168:169]
	s_mov_b32 m0, s40
	s_nop 0
	global_load_lds_dwordx4 v[208:209], off
	s_setprio 1
	s_waitcnt vmcnt(8)
	s_waitcnt lgkmcnt(0)
	s_barrier
	v_mfma_scale_f32_16x16x128_f8f6f4 v[160:163], v[28:35], v[192:199], v[160:163], v187, v185 op_sel_hi:[0,0,0]
	v_mfma_scale_f32_16x16x128_f8f6f4 v[156:159], v[20:27], v[192:199], v[156:159], v187, v185 op_sel_hi:[0,0,0]
	v_mfma_scale_f32_16x16x128_f8f6f4 v[144:147], v[28:35], v[200:207], v[144:147], v187, v185 op_sel_hi:[0,0,0]
	v_mfma_scale_f32_16x16x128_f8f6f4 v[140:143], v[20:27], v[200:207], v[140:143], v187, v185 op_sel_hi:[0,0,0]
	v_mfma_scale_f32_16x16x128_f8f6f4 v[128:131], v[28:35], v[216:223], v[128:131], v187, v185 op_sel_hi:[0,0,0]
	v_mfma_scale_f32_16x16x128_f8f6f4 v[124:127], v[20:27], v[216:223], v[124:127], v187, v185 op_sel_hi:[0,0,0]
	v_mfma_scale_f32_16x16x128_f8f6f4 v[112:115], v[28:35], v[224:231], v[112:115], v187, v185 op_sel_hi:[0,0,0]
	v_mfma_scale_f32_16x16x128_f8f6f4 v[108:111], v[20:27], v[224:231], v[108:111], v187, v185 op_sel_hi:[0,0,0]
	s_setprio 0
	s_setprio 1
	v_mfma_scale_f32_16x16x128_f8f6f4 v[152:155], v[12:19], v[192:199], v[152:155], v187, v185 op_sel_hi:[0,0,0]
	v_mfma_scale_f32_16x16x128_f8f6f4 v[148:151], v[4:11], v[192:199], v[148:151], v187, v185 op_sel_hi:[0,0,0]
	v_mfma_scale_f32_16x16x128_f8f6f4 v[136:139], v[12:19], v[200:207], v[136:139], v187, v185 op_sel_hi:[0,0,0]
	v_mfma_scale_f32_16x16x128_f8f6f4 v[132:135], v[4:11], v[200:207], v[132:135], v187, v185 op_sel_hi:[0,0,0]
	v_mfma_scale_f32_16x16x128_f8f6f4 v[120:123], v[12:19], v[216:223], v[120:123], v187, v185 op_sel_hi:[0,0,0]
	v_mfma_scale_f32_16x16x128_f8f6f4 v[116:119], v[4:11], v[216:223], v[116:119], v187, v185 op_sel_hi:[0,0,0]
	v_mfma_scale_f32_16x16x128_f8f6f4 v[104:107], v[12:19], v[224:231], v[104:107], v187, v185 op_sel_hi:[0,0,0]
	v_mfma_scale_f32_16x16x128_f8f6f4 v[100:103], v[4:11], v[224:231], v[100:103], v187, v185 op_sel_hi:[0,0,0]
	s_barrier
	s_setprio 0
	s_mov_b32 m0, s49
	v_lshl_add_u64 v[176:177], v[176:177], 0, s[64:65]
	s_add_u32 s10, s10, 0x40080
	ds_read_b128 v[192:195], v191 offset:49152
	ds_read_b128 v[196:199], v191 offset:49168
	ds_read_b128 v[200:203], v191 offset:51200
	ds_read_b128 v[204:207], v191 offset:51216
	ds_read_b128 v[216:219], v191 offset:53248
	ds_read_b128 v[220:223], v191 offset:53264
	ds_read_b128 v[224:227], v191 offset:55296
	ds_read_b128 v[228:231], v191 offset:55312
	global_load_lds_dwordx4 v[176:177], off
	v_lshl_add_u64 v[176:177], v[178:179], 0, s[64:65]
	s_mov_b32 m0, s84
	s_addc_u32 s11, s11, 0
	global_load_lds_dwordx4 v[176:177], off
	v_lshl_add_u64 v[176:177], s[10:11], 0, v[166:167]
	s_mov_b32 m0, s27
	s_nop 0
	global_load_lds_dwordx4 v[176:177], off
	v_lshl_add_u64 v[176:177], s[10:11], 0, v[170:171]
	s_mov_b32 m0, s48
	s_nop 0
	global_load_lds_dwordx4 v[176:177], off
	v_lshl_add_u64 v[176:177], v[180:181], 0, s[64:65]
	s_mov_b32 m0, s85
	s_nop 0
	global_load_lds_dwordx4 v[176:177], off
	v_lshl_add_u64 v[176:177], v[182:183], 0, s[64:65]
	s_mov_b32 m0, s26
	s_nop 0
	global_load_lds_dwordx4 v[176:177], off
	s_setprio 1
	s_waitcnt vmcnt(8)
	s_waitcnt lgkmcnt(0)
	s_barrier
	v_mfma_scale_f32_16x16x128_f8f6f4 v[96:99], v[28:35], v[192:199], v[96:99], v187, v185 op_sel_hi:[0,0,0]
	v_mfma_scale_f32_16x16x128_f8f6f4 v[92:95], v[20:27], v[192:199], v[92:95], v187, v185 op_sel_hi:[0,0,0]
	v_mfma_scale_f32_16x16x128_f8f6f4 v[80:83], v[28:35], v[200:207], v[80:83], v187, v185 op_sel_hi:[0,0,0]
	v_mfma_scale_f32_16x16x128_f8f6f4 v[76:79], v[20:27], v[200:207], v[76:79], v187, v185 op_sel_hi:[0,0,0]
	v_mfma_scale_f32_16x16x128_f8f6f4 v[64:67], v[28:35], v[216:223], v[64:67], v187, v185 op_sel_hi:[0,0,0]
	v_mfma_scale_f32_16x16x128_f8f6f4 v[60:63], v[20:27], v[216:223], v[60:63], v187, v185 op_sel_hi:[0,0,0]
	v_mfma_scale_f32_16x16x128_f8f6f4 v[48:51], v[28:35], v[224:231], v[48:51], v187, v185 op_sel_hi:[0,0,0]
	v_mfma_scale_f32_16x16x128_f8f6f4 v[44:47], v[20:27], v[224:231], v[44:47], v187, v185 op_sel_hi:[0,0,0]
	s_setprio 0
	s_setprio 1
	v_mfma_scale_f32_16x16x128_f8f6f4 v[88:91], v[12:19], v[192:199], v[88:91], v187, v185 op_sel_hi:[0,0,0]
	v_mfma_scale_f32_16x16x128_f8f6f4 v[84:87], v[4:11], v[192:199], v[84:87], v187, v185 op_sel_hi:[0,0,0]
	v_mfma_scale_f32_16x16x128_f8f6f4 v[72:75], v[12:19], v[200:207], v[72:75], v187, v185 op_sel_hi:[0,0,0]
	v_mfma_scale_f32_16x16x128_f8f6f4 v[68:71], v[4:11], v[200:207], v[68:71], v187, v185 op_sel_hi:[0,0,0]
	s_add_i32 s25, s25, 2
	v_mfma_scale_f32_16x16x128_f8f6f4 v[56:59], v[12:19], v[216:223], v[56:59], v187, v185 op_sel_hi:[0,0,0]
	s_add_u32 s8, s8, 0x100
	s_addc_u32 s9, s9, 0
	v_mfma_scale_f32_16x16x128_f8f6f4 v[52:55], v[4:11], v[216:223], v[52:55], v187, v185 op_sel_hi:[0,0,0]
	s_add_u32 s19, s19, 0x100
	s_addc_u32 s24, s24, 0
	v_mfma_scale_f32_16x16x128_f8f6f4 v[40:43], v[12:19], v[224:231], v[40:43], v187, v185 op_sel_hi:[0,0,0]
	s_cmp_gt_u32 s25, 13
	v_mfma_scale_f32_16x16x128_f8f6f4 v[36:39], v[4:11], v[224:231], v[36:39], v187, v185 op_sel_hi:[0,0,0]
	s_barrier
	s_setprio 0
	s_cbranch_scc0 .LBB0_1891
	v_readlane_b32 s8, v255, 13
	v_readlane_b32 s9, v255, 14
	s_and_b64 vcc, exec, s[8:9]
	s_cbranch_vccz .LBB0_1894
	s_barrier

.LBB0_2329:
	s_add_i32 s43, s12, 2
	v_add_u32_e32 v156, s83, v142
	v_add_u32_e32 v172, s44, v142
	s_add_u32 s10, s8, 0x100
	ds_read_b128 v[144:147], v156
	ds_read_b128 v[148:151], v156 offset:1024
	ds_read_b128 v[152:155], v156 offset:2048
	ds_read_b128 v[156:159], v156 offset:3072
	ds_read_b128 v[160:163], v172
	ds_read_b128 v[164:167], v172 offset:1024
	ds_read_b128 v[168:171], v172 offset:2048
	ds_read_b128 v[172:175], v172 offset:3072
	s_addc_u32 s11, s9, 0
	s_cmp_lg_u32 s42, s12
	s_cselect_b32 s46, s10, 0
	s_cselect_b32 s47, s11, 0
	s_add_u32 s12, s6, s46
	s_addc_u32 s13, s7, s47
	s_add_u32 s46, s4, s46
	s_addc_u32 s47, s5, s47
	v_lshl_add_u64 v[208:209], v[138:139], 0, s[8:9]
	s_add_i32 m0, s22, 0xc000
	ds_read_b128 v[176:179], v143
	ds_read_b128 v[180:183], v143 offset:1024
	ds_read_b128 v[184:187], v143 offset:2048
	ds_read_b128 v[188:191], v143 offset:3072
	ds_read_b128 v[192:195], v143 offset:4096
	ds_read_b128 v[196:199], v143 offset:5120
	ds_read_b128 v[200:203], v143 offset:6144
	ds_read_b128 v[204:207], v143 offset:7168
	global_load_lds_dwordx4 v[208:209], off
	v_lshl_add_u64 v[208:209], v[140:141], 0, s[8:9]
	s_add_i32 m0, s22, 0xe000
	s_nop 0
	global_load_lds_dwordx4 v[208:209], off
	s_setprio 1
	s_waitcnt vmcnt(8)
	s_waitcnt lgkmcnt(0)
	s_barrier
	v_mfma_f32_16x16x32_bf16 v[124:127], v[144:147], v[176:179], v[124:127]
	v_mfma_f32_16x16x32_bf16 v[124:127], v[148:151], v[180:183], v[124:127]
	v_mfma_f32_16x16x32_bf16 v[112:115], v[144:147], v[184:187], v[112:115]
	v_mfma_f32_16x16x32_bf16 v[112:115], v[148:151], v[188:191], v[112:115]
	v_mfma_f32_16x16x32_bf16 v[96:99], v[144:147], v[192:195], v[96:99]
	v_mfma_f32_16x16x32_bf16 v[96:99], v[148:151], v[196:199], v[96:99]
	v_mfma_f32_16x16x32_bf16 v[80:83], v[144:147], v[200:203], v[80:83]
	v_mfma_f32_16x16x32_bf16 v[80:83], v[148:151], v[204:207], v[80:83]
	v_mfma_f32_16x16x32_bf16 v[76:79], v[152:155], v[200:203], v[76:79]
	v_mfma_f32_16x16x32_bf16 v[76:79], v[156:159], v[204:207], v[76:79]
	v_mfma_f32_16x16x32_bf16 v[92:95], v[152:155], v[192:195], v[92:95]
	v_mfma_f32_16x16x32_bf16 v[92:95], v[156:159], v[196:199], v[92:95]
	v_mfma_f32_16x16x32_bf16 v[108:111], v[152:155], v[184:187], v[108:111]
	v_mfma_f32_16x16x32_bf16 v[108:111], v[156:159], v[188:191], v[108:111]
	v_mfma_f32_16x16x32_bf16 v[128:131], v[152:155], v[176:179], v[128:131]
	v_mfma_f32_16x16x32_bf16 v[128:131], v[156:159], v[180:183], v[128:131]
	s_setprio 0
	s_setprio 1
	v_mfma_f32_16x16x32_bf16 v[120:123], v[160:163], v[176:179], v[120:123]
	v_mfma_f32_16x16x32_bf16 v[120:123], v[164:167], v[180:183], v[120:123]
	v_mfma_f32_16x16x32_bf16 v[104:107], v[160:163], v[184:187], v[104:107]
	v_mfma_f32_16x16x32_bf16 v[104:107], v[164:167], v[188:191], v[104:107]
	v_mfma_f32_16x16x32_bf16 v[88:91], v[160:163], v[192:195], v[88:91]
	v_mfma_f32_16x16x32_bf16 v[88:91], v[164:167], v[196:199], v[88:91]
	v_mfma_f32_16x16x32_bf16 v[72:75], v[160:163], v[200:203], v[72:75]
	v_mfma_f32_16x16x32_bf16 v[72:75], v[164:167], v[204:207], v[72:75]
	v_mfma_f32_16x16x32_bf16 v[68:71], v[168:171], v[200:203], v[68:71]
	v_mfma_f32_16x16x32_bf16 v[68:71], v[172:175], v[204:207], v[68:71]
	v_mfma_f32_16x16x32_bf16 v[84:87], v[168:171], v[192:195], v[84:87]
	v_mfma_f32_16x16x32_bf16 v[84:87], v[172:175], v[196:199], v[84:87]
	v_mfma_f32_16x16x32_bf16 v[100:103], v[168:171], v[184:187], v[100:103]
	v_mfma_f32_16x16x32_bf16 v[100:103], v[172:175], v[188:191], v[100:103]
	v_mfma_f32_16x16x32_bf16 v[116:119], v[168:171], v[176:179], v[116:119]
	v_mfma_f32_16x16x32_bf16 v[116:119], v[172:175], v[180:183], v[116:119]
	s_barrier
	s_setprio 0
	s_mov_b32 m0, s18
	v_lshl_add_u64 v[208:209], s[46:47], 0, v[2:3]
	s_add_u32 s8, s46, s2
	ds_read_b128 v[176:179], v143 offset:16384
	ds_read_b128 v[180:183], v143 offset:17408
	ds_read_b128 v[184:187], v143 offset:18432
	ds_read_b128 v[188:191], v143 offset:19456
	ds_read_b128 v[192:195], v143 offset:20480
	ds_read_b128 v[196:199], v143 offset:21504
	ds_read_b128 v[200:203], v143 offset:22528
	ds_read_b128 v[204:207], v143 offset:23552
	global_load_lds_dwordx4 v[208:209], off
	v_lshl_add_u64 v[210:211], s[46:47], 0, v[136:137]
	s_mov_b32 m0, s19
	s_addc_u32 s9, s47, s3
	global_load_lds_dwordx4 v[210:211], off
	v_lshl_add_u64 v[216:217], s[8:9], 0, v[2:3]
	s_mov_b32 m0, s20
	v_lshl_add_u64 v[218:219], s[8:9], 0, v[136:137]
	global_load_lds_dwordx4 v[216:217], off
	s_mov_b32 m0, s21
	v_lshl_add_u64 v[220:221], s[12:13], 0, v[132:133]
	global_load_lds_dwordx4 v[218:219], off
	s_mov_b32 m0, s22
	v_lshl_add_u64 v[222:223], s[12:13], 0, v[134:135]
	global_load_lds_dwordx4 v[220:221], off
	s_mov_b32 m0, s23
	s_nop 0
	global_load_lds_dwordx4 v[222:223], off
	s_setprio 1
	s_waitcnt vmcnt(8)
	s_waitcnt lgkmcnt(0)
	s_barrier
	v_mfma_f32_16x16x32_bf16 v[64:67], v[144:147], v[176:179], v[64:67]
	v_mfma_f32_16x16x32_bf16 v[64:67], v[148:151], v[180:183], v[64:67]
	v_mfma_f32_16x16x32_bf16 v[48:51], v[144:147], v[184:187], v[48:51]
	v_mfma_f32_16x16x32_bf16 v[48:51], v[148:151], v[188:191], v[48:51]
	v_mfma_f32_16x16x32_bf16 v[32:35], v[144:147], v[192:195], v[32:35]
	v_mfma_f32_16x16x32_bf16 v[32:35], v[148:151], v[196:199], v[32:35]
	v_mfma_f32_16x16x32_bf16 v[16:19], v[144:147], v[200:203], v[16:19]
	v_mfma_f32_16x16x32_bf16 v[16:19], v[148:151], v[204:207], v[16:19]
	v_mfma_f32_16x16x32_bf16 v[12:15], v[152:155], v[200:203], v[12:15]
	v_mfma_f32_16x16x32_bf16 v[12:15], v[156:159], v[204:207], v[12:15]
	v_mfma_f32_16x16x32_bf16 v[28:31], v[152:155], v[192:195], v[28:31]
	v_mfma_f32_16x16x32_bf16 v[28:31], v[156:159], v[196:199], v[28:31]
	v_mfma_f32_16x16x32_bf16 v[44:47], v[152:155], v[184:187], v[44:47]
	v_mfma_f32_16x16x32_bf16 v[44:47], v[156:159], v[188:191], v[44:47]
	v_mfma_f32_16x16x32_bf16 v[60:63], v[152:155], v[176:179], v[60:63]
	v_mfma_f32_16x16x32_bf16 v[60:63], v[156:159], v[180:183], v[60:63]
	s_setprio 0
	s_setprio 1
	v_mfma_f32_16x16x32_bf16 v[56:59], v[160:163], v[176:179], v[56:59]
	v_mfma_f32_16x16x32_bf16 v[56:59], v[164:167], v[180:183], v[56:59]
	v_mfma_f32_16x16x32_bf16 v[40:43], v[160:163], v[184:187], v[40:43]
	v_mfma_f32_16x16x32_bf16 v[40:43], v[164:167], v[188:191], v[40:43]
	v_mfma_f32_16x16x32_bf16 v[24:27], v[160:163], v[192:195], v[24:27]
	v_mfma_f32_16x16x32_bf16 v[24:27], v[164:167], v[196:199], v[24:27]
	v_mfma_f32_16x16x32_bf16 v[8:11], v[160:163], v[200:203], v[8:11]
	v_mfma_f32_16x16x32_bf16 v[8:11], v[164:167], v[204:207], v[8:11]
	v_mfma_f32_16x16x32_bf16 v[4:7], v[168:171], v[200:203], v[4:7]
	v_mfma_f32_16x16x32_bf16 v[4:7], v[172:175], v[204:207], v[4:7]
	v_mfma_f32_16x16x32_bf16 v[20:23], v[168:171], v[192:195], v[20:23]
	v_mfma_f32_16x16x32_bf16 v[20:23], v[172:175], v[196:199], v[20:23]
	v_mfma_f32_16x16x32_bf16 v[36:39], v[168:171], v[184:187], v[36:39]
	v_mfma_f32_16x16x32_bf16 v[36:39], v[172:175], v[188:191], v[36:39]
	v_mfma_f32_16x16x32_bf16 v[52:55], v[168:171], v[176:179], v[52:55]
	v_mfma_f32_16x16x32_bf16 v[52:55], v[172:175], v[180:183], v[52:55]
	s_barrier
	s_setprio 0
	v_add_u32_e32 v156, s45, v142
	v_add_u32_e32 v172, s74, v142
	ds_read_b128 v[144:147], v156
	ds_read_b128 v[148:151], v156 offset:1024
	ds_read_b128 v[152:155], v156 offset:2048
	ds_read_b128 v[156:159], v156 offset:3072
	ds_read_b128 v[160:163], v172
	ds_read_b128 v[164:167], v172 offset:1024
	ds_read_b128 v[168:171], v172 offset:2048
	ds_read_b128 v[172:175], v172 offset:3072
	s_add_u32 s8, s12, s2
	s_addc_u32 s9, s13, s3
	s_mov_b32 m0, s24
	v_lshl_add_u64 v[224:225], s[8:9], 0, v[132:133]
	ds_read_b128 v[176:179], v143 offset:32768
	ds_read_b128 v[180:183], v143 offset:33792
	ds_read_b128 v[184:187], v143 offset:34816
	ds_read_b128 v[188:191], v143 offset:35840
	ds_read_b128 v[192:195], v143 offset:36864
	ds_read_b128 v[196:199], v143 offset:37888
	ds_read_b128 v[200:203], v143 offset:38912
	ds_read_b128 v[204:207], v143 offset:39936
	global_load_lds_dwordx4 v[224:225], off
	v_lshl_add_u64 v[224:225], s[8:9], 0, v[134:135]
	s_mov_b32 m0, s25
	s_nop 0
	global_load_lds_dwordx4 v[224:225], off
	s_setprio 1
	s_waitcnt vmcnt(8)
	s_waitcnt lgkmcnt(0)
	s_barrier
	v_mfma_f32_16x16x32_bf16 v[124:127], v[144:147], v[176:179], v[124:127]
	v_mfma_f32_16x16x32_bf16 v[124:127], v[148:151], v[180:183], v[124:127]
	v_mfma_f32_16x16x32_bf16 v[112:115], v[144:147], v[184:187], v[112:115]
	v_mfma_f32_16x16x32_bf16 v[112:115], v[148:151], v[188:191], v[112:115]
	v_mfma_f32_16x16x32_bf16 v[96:99], v[144:147], v[192:195], v[96:99]
	v_mfma_f32_16x16x32_bf16 v[96:99], v[148:151], v[196:199], v[96:99]
	v_mfma_f32_16x16x32_bf16 v[80:83], v[144:147], v[200:203], v[80:83]
	v_mfma_f32_16x16x32_bf16 v[80:83], v[148:151], v[204:207], v[80:83]
	v_mfma_f32_16x16x32_bf16 v[76:79], v[152:155], v[200:203], v[76:79]
	v_mfma_f32_16x16x32_bf16 v[76:79], v[156:159], v[204:207], v[76:79]
	v_mfma_f32_16x16x32_bf16 v[92:95], v[152:155], v[192:195], v[92:95]
	v_mfma_f32_16x16x32_bf16 v[92:95], v[156:159], v[196:199], v[92:95]
	v_mfma_f32_16x16x32_bf16 v[108:111], v[152:155], v[184:187], v[108:111]
	v_mfma_f32_16x16x32_bf16 v[108:111], v[156:159], v[188:191], v[108:111]
	v_mfma_f32_16x16x32_bf16 v[128:131], v[152:155], v[176:179], v[128:131]
	v_mfma_f32_16x16x32_bf16 v[128:131], v[156:159], v[180:183], v[128:131]
	s_setprio 0
	s_setprio 1
	v_mfma_f32_16x16x32_bf16 v[120:123], v[160:163], v[176:179], v[120:123]
	v_mfma_f32_16x16x32_bf16 v[120:123], v[164:167], v[180:183], v[120:123]
	v_mfma_f32_16x16x32_bf16 v[104:107], v[160:163], v[184:187], v[104:107]
	v_mfma_f32_16x16x32_bf16 v[104:107], v[164:167], v[188:191], v[104:107]
	v_mfma_f32_16x16x32_bf16 v[88:91], v[160:163], v[192:195], v[88:91]
	v_mfma_f32_16x16x32_bf16 v[88:91], v[164:167], v[196:199], v[88:91]
	v_mfma_f32_16x16x32_bf16 v[72:75], v[160:163], v[200:203], v[72:75]
	v_mfma_f32_16x16x32_bf16 v[72:75], v[164:167], v[204:207], v[72:75]
	v_mfma_f32_16x16x32_bf16 v[68:71], v[168:171], v[200:203], v[68:71]
	v_mfma_f32_16x16x32_bf16 v[68:71], v[172:175], v[204:207], v[68:71]
	v_mfma_f32_16x16x32_bf16 v[84:87], v[168:171], v[192:195], v[84:87]
	v_mfma_f32_16x16x32_bf16 v[84:87], v[172:175], v[196:199], v[84:87]
	v_mfma_f32_16x16x32_bf16 v[100:103], v[168:171], v[184:187], v[100:103]
	v_mfma_f32_16x16x32_bf16 v[100:103], v[172:175], v[188:191], v[100:103]
	v_mfma_f32_16x16x32_bf16 v[116:119], v[168:171], v[176:179], v[116:119]
	v_mfma_f32_16x16x32_bf16 v[116:119], v[172:175], v[180:183], v[116:119]
	s_barrier
	s_setprio 0
	s_mov_b32 m0, s26
	v_lshl_add_u64 v[208:209], v[208:209], 0, s[64:65]
	ds_read_b128 v[176:179], v143 offset:49152
	ds_read_b128 v[180:183], v143 offset:50176
	ds_read_b128 v[184:187], v143 offset:51200
	ds_read_b128 v[188:191], v143 offset:52224
	ds_read_b128 v[192:195], v143 offset:53248
	ds_read_b128 v[196:199], v143 offset:54272
	ds_read_b128 v[200:203], v143 offset:55296
	ds_read_b128 v[204:207], v143 offset:56320
	global_load_lds_dwordx4 v[208:209], off
	v_lshl_add_u64 v[208:209], v[210:211], 0, s[64:65]
	s_mov_b32 m0, s27
	s_nop 0
	global_load_lds_dwordx4 v[208:209], off
	v_lshl_add_u64 v[208:209], v[216:217], 0, s[64:65]
	s_mov_b32 m0, s37
	s_nop 0
	global_load_lds_dwordx4 v[208:209], off
	v_lshl_add_u64 v[208:209], v[218:219], 0, s[64:65]
	s_mov_b32 m0, s40
	s_nop 0
	global_load_lds_dwordx4 v[208:209], off
	v_lshl_add_u64 v[208:209], v[220:221], 0, s[64:65]
	s_mov_b32 m0, s34
	s_nop 0
	global_load_lds_dwordx4 v[208:209], off
	v_lshl_add_u64 v[208:209], v[222:223], 0, s[64:65]
	s_mov_b32 m0, s35
	s_nop 0
	global_load_lds_dwordx4 v[208:209], off
	s_setprio 1
	s_waitcnt vmcnt(8)
	s_waitcnt lgkmcnt(0)
	s_barrier
	v_mfma_f32_16x16x32_bf16 v[64:67], v[144:147], v[176:179], v[64:67]
	v_mfma_f32_16x16x32_bf16 v[64:67], v[148:151], v[180:183], v[64:67]
	v_mfma_f32_16x16x32_bf16 v[48:51], v[144:147], v[184:187], v[48:51]
	v_mfma_f32_16x16x32_bf16 v[48:51], v[148:151], v[188:191], v[48:51]
	v_mfma_f32_16x16x32_bf16 v[32:35], v[144:147], v[192:195], v[32:35]
	v_mfma_f32_16x16x32_bf16 v[32:35], v[148:151], v[196:199], v[32:35]
	v_mfma_f32_16x16x32_bf16 v[16:19], v[144:147], v[200:203], v[16:19]
	v_mfma_f32_16x16x32_bf16 v[16:19], v[148:151], v[204:207], v[16:19]
	v_mfma_f32_16x16x32_bf16 v[12:15], v[152:155], v[200:203], v[12:15]
	v_mfma_f32_16x16x32_bf16 v[12:15], v[156:159], v[204:207], v[12:15]
	v_mfma_f32_16x16x32_bf16 v[28:31], v[152:155], v[192:195], v[28:31]
	v_mfma_f32_16x16x32_bf16 v[28:31], v[156:159], v[196:199], v[28:31]
	v_mfma_f32_16x16x32_bf16 v[44:47], v[152:155], v[184:187], v[44:47]
	v_mfma_f32_16x16x32_bf16 v[44:47], v[156:159], v[188:191], v[44:47]
	v_mfma_f32_16x16x32_bf16 v[60:63], v[152:155], v[176:179], v[60:63]
	v_mfma_f32_16x16x32_bf16 v[60:63], v[156:159], v[180:183], v[60:63]
	s_setprio 0
	s_setprio 1
	v_mfma_f32_16x16x32_bf16 v[56:59], v[160:163], v[176:179], v[56:59]
	v_mfma_f32_16x16x32_bf16 v[56:59], v[164:167], v[180:183], v[56:59]
	v_mfma_f32_16x16x32_bf16 v[40:43], v[160:163], v[184:187], v[40:43]
	v_mfma_f32_16x16x32_bf16 v[40:43], v[164:167], v[188:191], v[40:43]
	v_mfma_f32_16x16x32_bf16 v[24:27], v[160:163], v[192:195], v[24:27]
	v_mfma_f32_16x16x32_bf16 v[24:27], v[164:167], v[196:199], v[24:27]
	v_mfma_f32_16x16x32_bf16 v[8:11], v[160:163], v[200:203], v[8:11]
	v_mfma_f32_16x16x32_bf16 v[8:11], v[164:167], v[204:207], v[8:11]
	v_mfma_f32_16x16x32_bf16 v[4:7], v[168:171], v[200:203], v[4:7]
	v_mfma_f32_16x16x32_bf16 v[4:7], v[172:175], v[204:207], v[4:7]
	v_mfma_f32_16x16x32_bf16 v[20:23], v[168:171], v[192:195], v[20:23]
	v_mfma_f32_16x16x32_bf16 v[20:23], v[172:175], v[196:199], v[20:23]
	v_mfma_f32_16x16x32_bf16 v[36:39], v[168:171], v[184:187], v[36:39]
	v_mfma_f32_16x16x32_bf16 v[36:39], v[172:175], v[188:191], v[36:39]
	v_mfma_f32_16x16x32_bf16 v[52:55], v[168:171], v[176:179], v[52:55]
	v_mfma_f32_16x16x32_bf16 v[52:55], v[172:175], v[180:183], v[52:55]
	s_barrier
	s_setprio 0
	s_cmp_ge_i32 s43, s41
	s_mov_b64 s[8:9], s[10:11]
	s_mov_b32 s12, s43
	s_cbranch_scc0 .LBB0_2329

.LBB0_2890:
	v_add_u32_e32 v4, s18, v184
	v_add_u32_e32 v8, s19, v184
	s_add_u32 s14, s48, s12
	ds_read_b128 v[28:31], v4
	ds_read_b128 v[32:35], v4 offset:16
	ds_read_b128 v[20:23], v4 offset:2048
	ds_read_b128 v[24:27], v4 offset:2064
	ds_read_b128 v[12:15], v8
	ds_read_b128 v[16:19], v8 offset:16
	ds_read_b128 v[4:7], v8 offset:2048
	ds_read_b128 v[8:11], v8 offset:2064
	s_addc_u32 s15, s49, s13
	s_add_u32 s14, s14, 0x45c00100
	s_addc_u32 s15, s15, 0
	s_add_u32 s53, s50, s12
	s_addc_u32 s56, s51, s13
	s_cmpk_eq_i32 s12, 0x700
	s_cselect_b32 s25, s11, s15
	s_cselect_b32 s24, s10, s14
	s_cselect_b32 s15, s3, s56
	s_cselect_b32 s14, s2, s53
	v_lshl_add_u64 v[210:211], v[170:171], 0, s[12:13]
	s_add_i32 m0, s37, 0xc000
	ds_read_b128 v[174:177], v185
	ds_read_b128 v[178:181], v185 offset:16
	ds_read_b128 v[186:189], v185 offset:2048
	ds_read_b128 v[190:193], v185 offset:2064
	ds_read_b128 v[194:197], v185 offset:4096
	ds_read_b128 v[198:201], v185 offset:4112
	ds_read_b128 v[202:205], v185 offset:6144
	ds_read_b128 v[206:209], v185 offset:6160
	global_load_lds_dwordx4 v[210:211], off
	v_lshl_add_u64 v[210:211], v[172:173], 0, s[12:13]
	s_add_i32 m0, s37, 0xe000
	s_nop 0
	global_load_lds_dwordx4 v[210:211], off
	s_setprio 1
	s_waitcnt vmcnt(8)
	s_waitcnt lgkmcnt(0)
	s_barrier
	v_mfma_scale_f32_16x16x128_f8f6f4 v[160:163], v[28:35], v[174:181], v[160:163], v183, v182 op_sel_hi:[0,0,0]
	v_mfma_scale_f32_16x16x128_f8f6f4 v[156:159], v[20:27], v[174:181], v[156:159], v183, v182 op_sel_hi:[0,0,0]
	v_mfma_scale_f32_16x16x128_f8f6f4 v[144:147], v[28:35], v[186:193], v[144:147], v183, v182 op_sel_hi:[0,0,0]
	v_mfma_scale_f32_16x16x128_f8f6f4 v[140:143], v[20:27], v[186:193], v[140:143], v183, v182 op_sel_hi:[0,0,0]
	v_mfma_scale_f32_16x16x128_f8f6f4 v[128:131], v[28:35], v[194:201], v[128:131], v183, v182 op_sel_hi:[0,0,0]
	v_mfma_scale_f32_16x16x128_f8f6f4 v[124:127], v[20:27], v[194:201], v[124:127], v183, v182 op_sel_hi:[0,0,0]
	v_mfma_scale_f32_16x16x128_f8f6f4 v[112:115], v[28:35], v[202:209], v[112:115], v183, v182 op_sel_hi:[0,0,0]
	v_mfma_scale_f32_16x16x128_f8f6f4 v[108:111], v[20:27], v[202:209], v[108:111], v183, v182 op_sel_hi:[0,0,0]
	s_setprio 0
	s_setprio 1
	v_mfma_scale_f32_16x16x128_f8f6f4 v[152:155], v[12:19], v[174:181], v[152:155], v183, v182 op_sel_hi:[0,0,0]
	v_mfma_scale_f32_16x16x128_f8f6f4 v[148:151], v[4:11], v[174:181], v[148:151], v183, v182 op_sel_hi:[0,0,0]
	v_mfma_scale_f32_16x16x128_f8f6f4 v[136:139], v[12:19], v[186:193], v[136:139], v183, v182 op_sel_hi:[0,0,0]
	v_mfma_scale_f32_16x16x128_f8f6f4 v[132:135], v[4:11], v[186:193], v[132:135], v183, v182 op_sel_hi:[0,0,0]
	v_mfma_scale_f32_16x16x128_f8f6f4 v[120:123], v[12:19], v[194:201], v[120:123], v183, v182 op_sel_hi:[0,0,0]
	v_mfma_scale_f32_16x16x128_f8f6f4 v[116:119], v[4:11], v[194:201], v[116:119], v183, v182 op_sel_hi:[0,0,0]
	v_mfma_scale_f32_16x16x128_f8f6f4 v[104:107], v[12:19], v[202:209], v[104:107], v183, v182 op_sel_hi:[0,0,0]
	v_mfma_scale_f32_16x16x128_f8f6f4 v[100:103], v[4:11], v[202:209], v[100:103], v183, v182 op_sel_hi:[0,0,0]
	s_barrier
	s_setprio 0
	s_mov_b32 m0, s23
	v_lshl_add_u64 v[174:175], s[14:15], 0, v[2:3]
	s_add_u32 s56, s14, 0x40000
	ds_read_b128 v[186:189], v185 offset:16384
	ds_read_b128 v[190:193], v185 offset:16400
	ds_read_b128 v[194:197], v185 offset:18432
	ds_read_b128 v[198:201], v185 offset:18448
	ds_read_b128 v[202:205], v185 offset:20480
	ds_read_b128 v[206:209], v185 offset:20496
	ds_read_b128 v[216:219], v185 offset:22528
	ds_read_b128 v[220:223], v185 offset:22544
	global_load_lds_dwordx4 v[174:175], off
	v_lshl_add_u64 v[176:177], s[14:15], 0, v[168:169]
	s_mov_b32 m0, s26
	s_addc_u32 s57, s15, 0
	global_load_lds_dwordx4 v[176:177], off
	v_lshl_add_u64 v[178:179], s[56:57], 0, v[2:3]
	s_mov_b32 m0, s27
	v_lshl_add_u64 v[180:181], s[24:25], 0, v[166:167]
	global_load_lds_dwordx4 v[178:179], off
	v_lshl_add_u64 v[178:179], s[56:57], 0, v[168:169]
	s_mov_b32 m0, s34
	s_nop 0
	global_load_lds_dwordx4 v[178:179], off
	v_lshl_add_u64 v[178:179], s[24:25], 0, v[164:165]
	s_mov_b32 m0, s37
	s_nop 0
	global_load_lds_dwordx4 v[178:179], off
	s_mov_b32 m0, s38
	s_nop 0
	global_load_lds_dwordx4 v[180:181], off
	s_setprio 1
	s_waitcnt vmcnt(8)
	s_waitcnt lgkmcnt(0)
	s_barrier
	v_mfma_scale_f32_16x16x128_f8f6f4 v[96:99], v[28:35], v[186:193], v[96:99], v183, v182 op_sel_hi:[0,0,0]
	v_mfma_scale_f32_16x16x128_f8f6f4 v[92:95], v[20:27], v[186:193], v[92:95], v183, v182 op_sel_hi:[0,0,0]
	v_mfma_scale_f32_16x16x128_f8f6f4 v[80:83], v[28:35], v[194:201], v[80:83], v183, v182 op_sel_hi:[0,0,0]
	v_mfma_scale_f32_16x16x128_f8f6f4 v[76:79], v[20:27], v[194:201], v[76:79], v183, v182 op_sel_hi:[0,0,0]
	v_mfma_scale_f32_16x16x128_f8f6f4 v[64:67], v[28:35], v[202:209], v[64:67], v183, v182 op_sel_hi:[0,0,0]
	v_mfma_scale_f32_16x16x128_f8f6f4 v[60:63], v[20:27], v[202:209], v[60:63], v183, v182 op_sel_hi:[0,0,0]
	v_mfma_scale_f32_16x16x128_f8f6f4 v[48:51], v[28:35], v[216:223], v[48:51], v183, v182 op_sel_hi:[0,0,0]
	v_mfma_scale_f32_16x16x128_f8f6f4 v[44:47], v[20:27], v[216:223], v[44:47], v183, v182 op_sel_hi:[0,0,0]
	s_setprio 0
	s_setprio 1
	v_mfma_scale_f32_16x16x128_f8f6f4 v[88:91], v[12:19], v[186:193], v[88:91], v183, v182 op_sel_hi:[0,0,0]
	v_mfma_scale_f32_16x16x128_f8f6f4 v[84:87], v[4:11], v[186:193], v[84:87], v183, v182 op_sel_hi:[0,0,0]
	v_mfma_scale_f32_16x16x128_f8f6f4 v[72:75], v[12:19], v[194:201], v[72:75], v183, v182 op_sel_hi:[0,0,0]
	v_mfma_scale_f32_16x16x128_f8f6f4 v[68:71], v[4:11], v[194:201], v[68:71], v183, v182 op_sel_hi:[0,0,0]
	v_mfma_scale_f32_16x16x128_f8f6f4 v[56:59], v[12:19], v[202:209], v[56:59], v183, v182 op_sel_hi:[0,0,0]
	v_mfma_scale_f32_16x16x128_f8f6f4 v[52:55], v[4:11], v[202:209], v[52:55], v183, v182 op_sel_hi:[0,0,0]
	v_mfma_scale_f32_16x16x128_f8f6f4 v[40:43], v[12:19], v[216:223], v[40:43], v183, v182 op_sel_hi:[0,0,0]
	v_mfma_scale_f32_16x16x128_f8f6f4 v[36:39], v[4:11], v[216:223], v[36:39], v183, v182 op_sel_hi:[0,0,0]
	s_barrier
	s_setprio 0
	v_add_u32_e32 v4, s20, v184
	v_add_u32_e32 v8, s21, v184
	ds_read_b128 v[28:31], v4
	ds_read_b128 v[32:35], v4 offset:16
	ds_read_b128 v[20:23], v4 offset:2048
	ds_read_b128 v[24:27], v4 offset:2064
	ds_read_b128 v[12:15], v8
	ds_read_b128 v[16:19], v8 offset:16
	ds_read_b128 v[4:7], v8 offset:2048
	ds_read_b128 v[8:11], v8 offset:2064
	s_add_u32 s24, s24, 0x40000
	s_addc_u32 s25, s25, 0
	s_mov_b32 m0, s39
	v_lshl_add_u64 v[210:211], s[24:25], 0, v[164:165]
	ds_read_b128 v[186:189], v185 offset:32768
	ds_read_b128 v[190:193], v185 offset:32784
	ds_read_b128 v[194:197], v185 offset:34816
	ds_read_b128 v[198:201], v185 offset:34832
	ds_read_b128 v[202:205], v185 offset:36864
	ds_read_b128 v[206:209], v185 offset:36880
	ds_read_b128 v[216:219], v185 offset:38912
	ds_read_b128 v[220:223], v185 offset:38928
	global_load_lds_dwordx4 v[210:211], off
	v_lshl_add_u64 v[210:211], s[24:25], 0, v[166:167]
	s_mov_b32 m0, s40
	s_nop 0
	global_load_lds_dwordx4 v[210:211], off
	s_setprio 1
	s_waitcnt vmcnt(8)
	s_waitcnt lgkmcnt(0)
	s_barrier
	v_mfma_scale_f32_16x16x128_f8f6f4 v[160:163], v[28:35], v[186:193], v[160:163], v183, v182 op_sel_hi:[0,0,0]
	v_mfma_scale_f32_16x16x128_f8f6f4 v[156:159], v[20:27], v[186:193], v[156:159], v183, v182 op_sel_hi:[0,0,0]
	v_mfma_scale_f32_16x16x128_f8f6f4 v[144:147], v[28:35], v[194:201], v[144:147], v183, v182 op_sel_hi:[0,0,0]
	v_mfma_scale_f32_16x16x128_f8f6f4 v[140:143], v[20:27], v[194:201], v[140:143], v183, v182 op_sel_hi:[0,0,0]
	v_mfma_scale_f32_16x16x128_f8f6f4 v[128:131], v[28:35], v[202:209], v[128:131], v183, v182 op_sel_hi:[0,0,0]
	v_mfma_scale_f32_16x16x128_f8f6f4 v[124:127], v[20:27], v[202:209], v[124:127], v183, v182 op_sel_hi:[0,0,0]
	v_mfma_scale_f32_16x16x128_f8f6f4 v[112:115], v[28:35], v[216:223], v[112:115], v183, v182 op_sel_hi:[0,0,0]
	v_mfma_scale_f32_16x16x128_f8f6f4 v[108:111], v[20:27], v[216:223], v[108:111], v183, v182 op_sel_hi:[0,0,0]
	s_setprio 0
	s_setprio 1
	v_mfma_scale_f32_16x16x128_f8f6f4 v[152:155], v[12:19], v[186:193], v[152:155], v183, v182 op_sel_hi:[0,0,0]
	v_mfma_scale_f32_16x16x128_f8f6f4 v[148:151], v[4:11], v[186:193], v[148:151], v183, v182 op_sel_hi:[0,0,0]
	v_mfma_scale_f32_16x16x128_f8f6f4 v[136:139], v[12:19], v[194:201], v[136:139], v183, v182 op_sel_hi:[0,0,0]
	v_mfma_scale_f32_16x16x128_f8f6f4 v[132:135], v[4:11], v[194:201], v[132:135], v183, v182 op_sel_hi:[0,0,0]
	v_mfma_scale_f32_16x16x128_f8f6f4 v[120:123], v[12:19], v[202:209], v[120:123], v183, v182 op_sel_hi:[0,0,0]
	v_mfma_scale_f32_16x16x128_f8f6f4 v[116:119], v[4:11], v[202:209], v[116:119], v183, v182 op_sel_hi:[0,0,0]
	v_mfma_scale_f32_16x16x128_f8f6f4 v[104:107], v[12:19], v[216:223], v[104:107], v183, v182 op_sel_hi:[0,0,0]
	v_mfma_scale_f32_16x16x128_f8f6f4 v[100:103], v[4:11], v[216:223], v[100:103], v183, v182 op_sel_hi:[0,0,0]
	s_barrier
	s_setprio 0
	s_mov_b32 m0, s42
	v_lshl_add_u64 v[174:175], v[174:175], 0, s[64:65]
	s_add_u32 s14, s14, 0x40080
	ds_read_b128 v[186:189], v185 offset:49152
	ds_read_b128 v[190:193], v185 offset:49168
	ds_read_b128 v[194:197], v185 offset:51200
	ds_read_b128 v[198:201], v185 offset:51216
	ds_read_b128 v[202:205], v185 offset:53248
	ds_read_b128 v[206:209], v185 offset:53264
	ds_read_b128 v[216:219], v185 offset:55296
	ds_read_b128 v[220:223], v185 offset:55312
	global_load_lds_dwordx4 v[174:175], off
	v_lshl_add_u64 v[174:175], v[176:177], 0, s[64:65]
	s_mov_b32 m0, s43
	s_addc_u32 s15, s15, 0
	global_load_lds_dwordx4 v[174:175], off
	v_lshl_add_u64 v[174:175], s[14:15], 0, v[2:3]
	s_mov_b32 m0, s46
	s_nop 0
	global_load_lds_dwordx4 v[174:175], off
	v_lshl_add_u64 v[174:175], s[14:15], 0, v[168:169]
	s_mov_b32 m0, s47
	s_nop 0
	global_load_lds_dwordx4 v[174:175], off
	v_lshl_add_u64 v[174:175], v[178:179], 0, s[64:65]
	s_mov_b32 m0, s44
	s_nop 0
	global_load_lds_dwordx4 v[174:175], off
	v_lshl_add_u64 v[174:175], v[180:181], 0, s[64:65]
	s_mov_b32 m0, s45
	s_nop 0
	global_load_lds_dwordx4 v[174:175], off
	s_setprio 1
	s_waitcnt vmcnt(8)
	s_waitcnt lgkmcnt(0)
	s_barrier
	v_mfma_scale_f32_16x16x128_f8f6f4 v[96:99], v[28:35], v[186:193], v[96:99], v183, v182 op_sel_hi:[0,0,0]
	v_mfma_scale_f32_16x16x128_f8f6f4 v[92:95], v[20:27], v[186:193], v[92:95], v183, v182 op_sel_hi:[0,0,0]
	v_mfma_scale_f32_16x16x128_f8f6f4 v[80:83], v[28:35], v[194:201], v[80:83], v183, v182 op_sel_hi:[0,0,0]
	v_mfma_scale_f32_16x16x128_f8f6f4 v[76:79], v[20:27], v[194:201], v[76:79], v183, v182 op_sel_hi:[0,0,0]
	v_mfma_scale_f32_16x16x128_f8f6f4 v[64:67], v[28:35], v[202:209], v[64:67], v183, v182 op_sel_hi:[0,0,0]
	v_mfma_scale_f32_16x16x128_f8f6f4 v[60:63], v[20:27], v[202:209], v[60:63], v183, v182 op_sel_hi:[0,0,0]
	v_mfma_scale_f32_16x16x128_f8f6f4 v[48:51], v[28:35], v[216:223], v[48:51], v183, v182 op_sel_hi:[0,0,0]
	v_mfma_scale_f32_16x16x128_f8f6f4 v[44:47], v[20:27], v[216:223], v[44:47], v183, v182 op_sel_hi:[0,0,0]
	s_setprio 0
	s_setprio 1
	v_mfma_scale_f32_16x16x128_f8f6f4 v[88:91], v[12:19], v[186:193], v[88:91], v183, v182 op_sel_hi:[0,0,0]
	v_mfma_scale_f32_16x16x128_f8f6f4 v[84:87], v[4:11], v[186:193], v[84:87], v183, v182 op_sel_hi:[0,0,0]
	v_mfma_scale_f32_16x16x128_f8f6f4 v[72:75], v[12:19], v[194:201], v[72:75], v183, v182 op_sel_hi:[0,0,0]
	v_mfma_scale_f32_16x16x128_f8f6f4 v[68:71], v[4:11], v[194:201], v[68:71], v183, v182 op_sel_hi:[0,0,0]
	s_add_i32 s52, s52, 2
	v_mfma_scale_f32_16x16x128_f8f6f4 v[56:59], v[12:19], v[202:209], v[56:59], v183, v182 op_sel_hi:[0,0,0]
	s_add_u32 s12, s12, 0x100
	s_addc_u32 s13, s13, 0
	v_mfma_scale_f32_16x16x128_f8f6f4 v[52:55], v[4:11], v[202:209], v[52:55], v183, v182 op_sel_hi:[0,0,0]
	s_cmp_gt_u32 s52, 13
	v_mfma_scale_f32_16x16x128_f8f6f4 v[40:43], v[12:19], v[216:223], v[40:43], v183, v182 op_sel_hi:[0,0,0]
	v_mfma_scale_f32_16x16x128_f8f6f4 v[36:39], v[4:11], v[216:223], v[36:39], v183, v182 op_sel_hi:[0,0,0]
	s_barrier
	s_setprio 0
	s_cbranch_scc0 .LBB0_2890
	s_cmpk_lt_u32 s22, 0x100
	s_cbranch_scc0 .LBB0_2893
	s_barrier

.LBB0_2896:
	v_add_u32_e32 v148, s18, v126
	v_add_u32_e32 v172, s19, v126
	s_add_u32 s12, s46, s8
	ds_read_b128 v[128:131], v148
	ds_read_b128 v[132:135], v148 offset:1024
	ds_read_b128 v[140:143], v148 offset:2048
	ds_read_b128 v[148:151], v148 offset:3072
	ds_read_b128 v[160:163], v172
	ds_read_b128 v[164:167], v172 offset:1024
	ds_read_b128 v[168:171], v172 offset:2048
	ds_read_b128 v[172:175], v172 offset:3072
	s_addc_u32 s13, s47, s9
	s_add_u32 s12, s12, 0x34400100
	s_addc_u32 s13, s13, 0
	s_add_u32 s16, s48, s8
	s_addc_u32 s51, s49, s9
	s_cmpk_eq_i32 s8, 0xf00
	s_cselect_b32 s15, s11, s13
	s_cselect_b32 s14, s10, s12
	s_cselect_b32 s13, s3, s51
	s_cselect_b32 s12, s2, s16
	v_lshl_add_u64 v[208:209], v[122:123], 0, s[8:9]
	s_add_i32 m0, s27, 0xc000
	ds_read_b128 v[176:179], v127
	ds_read_b128 v[180:183], v127 offset:1024
	ds_read_b128 v[184:187], v127 offset:2048
	ds_read_b128 v[188:191], v127 offset:3072
	ds_read_b128 v[192:195], v127 offset:4096
	ds_read_b128 v[196:199], v127 offset:5120
	ds_read_b128 v[200:203], v127 offset:6144
	ds_read_b128 v[204:207], v127 offset:7168
	global_load_lds_dwordx4 v[208:209], off
	v_lshl_add_u64 v[208:209], v[124:125], 0, s[8:9]
	s_add_i32 m0, s27, 0xe000
	s_nop 0
	global_load_lds_dwordx4 v[208:209], off
	s_setprio 1
	s_waitcnt vmcnt(8)
	s_waitcnt lgkmcnt(0)
	s_barrier
	v_mfma_f32_16x16x32_bf16 v[156:159], v[128:131], v[176:179], v[156:159]
	v_mfma_f32_16x16x32_bf16 v[156:159], v[132:135], v[180:183], v[156:159]
	v_mfma_f32_16x16x32_bf16 v[112:115], v[128:131], v[184:187], v[112:115]
	v_mfma_f32_16x16x32_bf16 v[112:115], v[132:135], v[188:191], v[112:115]
	v_mfma_f32_16x16x32_bf16 v[96:99], v[128:131], v[192:195], v[96:99]
	v_mfma_f32_16x16x32_bf16 v[96:99], v[132:135], v[196:199], v[96:99]
	v_mfma_f32_16x16x32_bf16 v[80:83], v[128:131], v[200:203], v[80:83]
	v_mfma_f32_16x16x32_bf16 v[80:83], v[132:135], v[204:207], v[80:83]
	v_mfma_f32_16x16x32_bf16 v[76:79], v[140:143], v[200:203], v[76:79]
	v_mfma_f32_16x16x32_bf16 v[76:79], v[148:151], v[204:207], v[76:79]
	v_mfma_f32_16x16x32_bf16 v[92:95], v[140:143], v[192:195], v[92:95]
	v_mfma_f32_16x16x32_bf16 v[92:95], v[148:151], v[196:199], v[92:95]
	v_mfma_f32_16x16x32_bf16 v[108:111], v[140:143], v[184:187], v[108:111]
	v_mfma_f32_16x16x32_bf16 v[108:111], v[148:151], v[188:191], v[108:111]
	v_mfma_f32_16x16x32_bf16 v[152:155], v[140:143], v[176:179], v[152:155]
	v_mfma_f32_16x16x32_bf16 v[152:155], v[148:151], v[180:183], v[152:155]
	s_setprio 0
	s_setprio 1
	v_mfma_f32_16x16x32_bf16 v[144:147], v[160:163], v[176:179], v[144:147]
	v_mfma_f32_16x16x32_bf16 v[144:147], v[164:167], v[180:183], v[144:147]
	v_mfma_f32_16x16x32_bf16 v[104:107], v[160:163], v[184:187], v[104:107]
	v_mfma_f32_16x16x32_bf16 v[104:107], v[164:167], v[188:191], v[104:107]
	v_mfma_f32_16x16x32_bf16 v[88:91], v[160:163], v[192:195], v[88:91]
	v_mfma_f32_16x16x32_bf16 v[88:91], v[164:167], v[196:199], v[88:91]
	v_mfma_f32_16x16x32_bf16 v[72:75], v[160:163], v[200:203], v[72:75]
	v_mfma_f32_16x16x32_bf16 v[72:75], v[164:167], v[204:207], v[72:75]
	v_mfma_f32_16x16x32_bf16 v[68:71], v[168:171], v[200:203], v[68:71]
	v_mfma_f32_16x16x32_bf16 v[68:71], v[172:175], v[204:207], v[68:71]
	v_mfma_f32_16x16x32_bf16 v[84:87], v[168:171], v[192:195], v[84:87]
	v_mfma_f32_16x16x32_bf16 v[84:87], v[172:175], v[196:199], v[84:87]
	v_mfma_f32_16x16x32_bf16 v[100:103], v[168:171], v[184:187], v[100:103]
	v_mfma_f32_16x16x32_bf16 v[100:103], v[172:175], v[188:191], v[100:103]
	v_mfma_f32_16x16x32_bf16 v[136:139], v[168:171], v[176:179], v[136:139]
	v_mfma_f32_16x16x32_bf16 v[136:139], v[172:175], v[180:183], v[136:139]
	s_barrier
	s_setprio 0
	s_mov_b32 m0, s23
	v_lshl_add_u64 v[208:209], s[12:13], 0, v[2:3]
	s_add_u32 s52, s12, 0x80000
	ds_read_b128 v[176:179], v127 offset:16384
	ds_read_b128 v[180:183], v127 offset:17408
	ds_read_b128 v[184:187], v127 offset:18432
	ds_read_b128 v[188:191], v127 offset:19456
	ds_read_b128 v[192:195], v127 offset:20480
	ds_read_b128 v[196:199], v127 offset:21504
	ds_read_b128 v[200:203], v127 offset:22528
	ds_read_b128 v[204:207], v127 offset:23552
	global_load_lds_dwordx4 v[208:209], off
	v_lshl_add_u64 v[210:211], s[12:13], 0, v[120:121]
	s_mov_b32 m0, s24
	s_addc_u32 s53, s13, 0
	global_load_lds_dwordx4 v[210:211], off
	v_lshl_add_u64 v[216:217], s[52:53], 0, v[2:3]
	s_mov_b32 m0, s25
	v_lshl_add_u64 v[218:219], s[14:15], 0, v[118:119]
	global_load_lds_dwordx4 v[216:217], off
	v_lshl_add_u64 v[216:217], s[52:53], 0, v[120:121]
	s_mov_b32 m0, s26
	s_nop 0
	global_load_lds_dwordx4 v[216:217], off
	v_lshl_add_u64 v[216:217], s[14:15], 0, v[116:117]
	s_mov_b32 m0, s27
	s_nop 0
	global_load_lds_dwordx4 v[216:217], off
	s_mov_b32 m0, s35
	s_nop 0
	global_load_lds_dwordx4 v[218:219], off
	s_setprio 1
	s_waitcnt vmcnt(8)
	s_waitcnt lgkmcnt(0)
	s_barrier
	v_mfma_f32_16x16x32_bf16 v[64:67], v[128:131], v[176:179], v[64:67]
	v_mfma_f32_16x16x32_bf16 v[64:67], v[132:135], v[180:183], v[64:67]
	v_mfma_f32_16x16x32_bf16 v[48:51], v[128:131], v[184:187], v[48:51]
	v_mfma_f32_16x16x32_bf16 v[48:51], v[132:135], v[188:191], v[48:51]
	v_mfma_f32_16x16x32_bf16 v[32:35], v[128:131], v[192:195], v[32:35]
	v_mfma_f32_16x16x32_bf16 v[32:35], v[132:135], v[196:199], v[32:35]
	v_mfma_f32_16x16x32_bf16 v[16:19], v[128:131], v[200:203], v[16:19]
	v_mfma_f32_16x16x32_bf16 v[16:19], v[132:135], v[204:207], v[16:19]
	v_mfma_f32_16x16x32_bf16 v[12:15], v[140:143], v[200:203], v[12:15]
	v_mfma_f32_16x16x32_bf16 v[12:15], v[148:151], v[204:207], v[12:15]
	v_mfma_f32_16x16x32_bf16 v[28:31], v[140:143], v[192:195], v[28:31]
	v_mfma_f32_16x16x32_bf16 v[28:31], v[148:151], v[196:199], v[28:31]
	v_mfma_f32_16x16x32_bf16 v[44:47], v[140:143], v[184:187], v[44:47]
	v_mfma_f32_16x16x32_bf16 v[44:47], v[148:151], v[188:191], v[44:47]
	v_mfma_f32_16x16x32_bf16 v[60:63], v[140:143], v[176:179], v[60:63]
	v_mfma_f32_16x16x32_bf16 v[60:63], v[148:151], v[180:183], v[60:63]
	s_setprio 0
	s_setprio 1
	v_mfma_f32_16x16x32_bf16 v[56:59], v[160:163], v[176:179], v[56:59]
	v_mfma_f32_16x16x32_bf16 v[56:59], v[164:167], v[180:183], v[56:59]
	v_mfma_f32_16x16x32_bf16 v[40:43], v[160:163], v[184:187], v[40:43]
	v_mfma_f32_16x16x32_bf16 v[40:43], v[164:167], v[188:191], v[40:43]
	v_mfma_f32_16x16x32_bf16 v[24:27], v[160:163], v[192:195], v[24:27]
	v_mfma_f32_16x16x32_bf16 v[24:27], v[164:167], v[196:199], v[24:27]
	v_mfma_f32_16x16x32_bf16 v[8:11], v[160:163], v[200:203], v[8:11]
	v_mfma_f32_16x16x32_bf16 v[8:11], v[164:167], v[204:207], v[8:11]
	v_mfma_f32_16x16x32_bf16 v[4:7], v[168:171], v[200:203], v[4:7]
	v_mfma_f32_16x16x32_bf16 v[4:7], v[172:175], v[204:207], v[4:7]
	v_mfma_f32_16x16x32_bf16 v[20:23], v[168:171], v[192:195], v[20:23]
	v_mfma_f32_16x16x32_bf16 v[20:23], v[172:175], v[196:199], v[20:23]
	v_mfma_f32_16x16x32_bf16 v[36:39], v[168:171], v[184:187], v[36:39]
	v_mfma_f32_16x16x32_bf16 v[36:39], v[172:175], v[188:191], v[36:39]
	v_mfma_f32_16x16x32_bf16 v[52:55], v[168:171], v[176:179], v[52:55]
	v_mfma_f32_16x16x32_bf16 v[52:55], v[172:175], v[180:183], v[52:55]
	s_barrier
	s_setprio 0
	v_add_u32_e32 v148, s20, v126
	v_add_u32_e32 v172, s21, v126
	ds_read_b128 v[128:131], v148
	ds_read_b128 v[132:135], v148 offset:1024
	ds_read_b128 v[140:143], v148 offset:2048
	ds_read_b128 v[148:151], v148 offset:3072
	ds_read_b128 v[160:163], v172
	ds_read_b128 v[164:167], v172 offset:1024
	ds_read_b128 v[168:171], v172 offset:2048
	ds_read_b128 v[172:175], v172 offset:3072
	s_add_u32 s14, s14, 0x80000
	s_addc_u32 s15, s15, 0
	s_mov_b32 m0, s37
	v_lshl_add_u64 v[220:221], s[14:15], 0, v[116:117]
	ds_read_b128 v[176:179], v127 offset:32768
	ds_read_b128 v[180:183], v127 offset:33792
	ds_read_b128 v[184:187], v127 offset:34816
	ds_read_b128 v[188:191], v127 offset:35840
	ds_read_b128 v[192:195], v127 offset:36864
	ds_read_b128 v[196:199], v127 offset:37888
	ds_read_b128 v[200:203], v127 offset:38912
	ds_read_b128 v[204:207], v127 offset:39936
	global_load_lds_dwordx4 v[220:221], off
	v_lshl_add_u64 v[220:221], s[14:15], 0, v[118:119]
	s_mov_b32 m0, s38
	s_nop 0
	global_load_lds_dwordx4 v[220:221], off
	s_setprio 1
	s_waitcnt vmcnt(8)
	s_waitcnt lgkmcnt(0)
	s_barrier
	v_mfma_f32_16x16x32_bf16 v[156:159], v[128:131], v[176:179], v[156:159]
	v_mfma_f32_16x16x32_bf16 v[156:159], v[132:135], v[180:183], v[156:159]
	v_mfma_f32_16x16x32_bf16 v[112:115], v[128:131], v[184:187], v[112:115]
	v_mfma_f32_16x16x32_bf16 v[112:115], v[132:135], v[188:191], v[112:115]
	v_mfma_f32_16x16x32_bf16 v[96:99], v[128:131], v[192:195], v[96:99]
	v_mfma_f32_16x16x32_bf16 v[96:99], v[132:135], v[196:199], v[96:99]
	v_mfma_f32_16x16x32_bf16 v[80:83], v[128:131], v[200:203], v[80:83]
	v_mfma_f32_16x16x32_bf16 v[80:83], v[132:135], v[204:207], v[80:83]
	v_mfma_f32_16x16x32_bf16 v[76:79], v[140:143], v[200:203], v[76:79]
	v_mfma_f32_16x16x32_bf16 v[76:79], v[148:151], v[204:207], v[76:79]
	v_mfma_f32_16x16x32_bf16 v[92:95], v[140:143], v[192:195], v[92:95]
	v_mfma_f32_16x16x32_bf16 v[92:95], v[148:151], v[196:199], v[92:95]
	v_mfma_f32_16x16x32_bf16 v[108:111], v[140:143], v[184:187], v[108:111]
	v_mfma_f32_16x16x32_bf16 v[108:111], v[148:151], v[188:191], v[108:111]
	v_mfma_f32_16x16x32_bf16 v[152:155], v[140:143], v[176:179], v[152:155]
	v_mfma_f32_16x16x32_bf16 v[152:155], v[148:151], v[180:183], v[152:155]
	s_setprio 0
	s_setprio 1
	v_mfma_f32_16x16x32_bf16 v[144:147], v[160:163], v[176:179], v[144:147]
	v_mfma_f32_16x16x32_bf16 v[144:147], v[164:167], v[180:183], v[144:147]
	v_mfma_f32_16x16x32_bf16 v[104:107], v[160:163], v[184:187], v[104:107]
	v_mfma_f32_16x16x32_bf16 v[104:107], v[164:167], v[188:191], v[104:107]
	v_mfma_f32_16x16x32_bf16 v[88:91], v[160:163], v[192:195], v[88:91]
	v_mfma_f32_16x16x32_bf16 v[88:91], v[164:167], v[196:199], v[88:91]
	v_mfma_f32_16x16x32_bf16 v[72:75], v[160:163], v[200:203], v[72:75]
	v_mfma_f32_16x16x32_bf16 v[72:75], v[164:167], v[204:207], v[72:75]
	v_mfma_f32_16x16x32_bf16 v[68:71], v[168:171], v[200:203], v[68:71]
	v_mfma_f32_16x16x32_bf16 v[68:71], v[172:175], v[204:207], v[68:71]
	v_mfma_f32_16x16x32_bf16 v[84:87], v[168:171], v[192:195], v[84:87]
	v_mfma_f32_16x16x32_bf16 v[84:87], v[172:175], v[196:199], v[84:87]
	v_mfma_f32_16x16x32_bf16 v[100:103], v[168:171], v[184:187], v[100:103]
	v_mfma_f32_16x16x32_bf16 v[100:103], v[172:175], v[188:191], v[100:103]
	v_mfma_f32_16x16x32_bf16 v[136:139], v[168:171], v[176:179], v[136:139]
	v_mfma_f32_16x16x32_bf16 v[136:139], v[172:175], v[180:183], v[136:139]
	s_barrier
	s_setprio 0
	s_mov_b32 m0, s40
	v_lshl_add_u64 v[208:209], v[208:209], 0, s[64:65]
	s_add_u32 s12, s12, 0x80080
	ds_read_b128 v[176:179], v127 offset:49152
	ds_read_b128 v[180:183], v127 offset:50176
	ds_read_b128 v[184:187], v127 offset:51200
	ds_read_b128 v[188:191], v127 offset:52224
	ds_read_b128 v[192:195], v127 offset:53248
	ds_read_b128 v[196:199], v127 offset:54272
	ds_read_b128 v[200:203], v127 offset:55296
	ds_read_b128 v[204:207], v127 offset:56320
	global_load_lds_dwordx4 v[208:209], off
	v_lshl_add_u64 v[208:209], v[210:211], 0, s[64:65]
	s_mov_b32 m0, s41
	s_addc_u32 s13, s13, 0
	global_load_lds_dwordx4 v[208:209], off
	v_lshl_add_u64 v[208:209], s[12:13], 0, v[2:3]
	s_mov_b32 m0, s44
	s_nop 0
	global_load_lds_dwordx4 v[208:209], off
	v_lshl_add_u64 v[208:209], s[12:13], 0, v[120:121]
	s_mov_b32 m0, s45
	s_nop 0
	global_load_lds_dwordx4 v[208:209], off
	v_lshl_add_u64 v[208:209], v[216:217], 0, s[64:65]
	s_mov_b32 m0, s42
	s_nop 0
	global_load_lds_dwordx4 v[208:209], off
	v_lshl_add_u64 v[208:209], v[218:219], 0, s[64:65]
	s_mov_b32 m0, s43
	s_nop 0
	global_load_lds_dwordx4 v[208:209], off
	s_setprio 1
	s_waitcnt vmcnt(8)
	s_waitcnt lgkmcnt(0)
	s_barrier
	v_mfma_f32_16x16x32_bf16 v[64:67], v[128:131], v[176:179], v[64:67]
	v_mfma_f32_16x16x32_bf16 v[64:67], v[132:135], v[180:183], v[64:67]
	v_mfma_f32_16x16x32_bf16 v[48:51], v[128:131], v[184:187], v[48:51]
	v_mfma_f32_16x16x32_bf16 v[48:51], v[132:135], v[188:191], v[48:51]
	v_mfma_f32_16x16x32_bf16 v[32:35], v[128:131], v[192:195], v[32:35]
	v_mfma_f32_16x16x32_bf16 v[32:35], v[132:135], v[196:199], v[32:35]
	v_mfma_f32_16x16x32_bf16 v[16:19], v[128:131], v[200:203], v[16:19]
	v_mfma_f32_16x16x32_bf16 v[16:19], v[132:135], v[204:207], v[16:19]
	v_mfma_f32_16x16x32_bf16 v[12:15], v[140:143], v[200:203], v[12:15]
	v_mfma_f32_16x16x32_bf16 v[12:15], v[148:151], v[204:207], v[12:15]
	v_mfma_f32_16x16x32_bf16 v[28:31], v[140:143], v[192:195], v[28:31]
	v_mfma_f32_16x16x32_bf16 v[28:31], v[148:151], v[196:199], v[28:31]
	v_mfma_f32_16x16x32_bf16 v[44:47], v[140:143], v[184:187], v[44:47]
	v_mfma_f32_16x16x32_bf16 v[44:47], v[148:151], v[188:191], v[44:47]
	v_mfma_f32_16x16x32_bf16 v[60:63], v[140:143], v[176:179], v[60:63]
	v_mfma_f32_16x16x32_bf16 v[60:63], v[148:151], v[180:183], v[60:63]
	s_setprio 0
	s_setprio 1
	v_mfma_f32_16x16x32_bf16 v[56:59], v[160:163], v[176:179], v[56:59]
	v_mfma_f32_16x16x32_bf16 v[56:59], v[164:167], v[180:183], v[56:59]
	v_mfma_f32_16x16x32_bf16 v[40:43], v[160:163], v[184:187], v[40:43]
	v_mfma_f32_16x16x32_bf16 v[40:43], v[164:167], v[188:191], v[40:43]
	v_mfma_f32_16x16x32_bf16 v[24:27], v[160:163], v[192:195], v[24:27]
	v_mfma_f32_16x16x32_bf16 v[24:27], v[164:167], v[196:199], v[24:27]
	v_mfma_f32_16x16x32_bf16 v[8:11], v[160:163], v[200:203], v[8:11]
	v_mfma_f32_16x16x32_bf16 v[8:11], v[164:167], v[204:207], v[8:11]
	s_add_i32 s50, s50, 2
	v_mfma_f32_16x16x32_bf16 v[4:7], v[168:171], v[200:203], v[4:7]
	v_mfma_f32_16x16x32_bf16 v[4:7], v[172:175], v[204:207], v[4:7]
	s_add_u32 s8, s8, 0x100
	s_addc_u32 s9, s9, 0
	v_mfma_f32_16x16x32_bf16 v[20:23], v[168:171], v[192:195], v[20:23]
	v_mfma_f32_16x16x32_bf16 v[20:23], v[172:175], v[196:199], v[20:23]
	s_cmp_gt_u32 s50, 29
	v_mfma_f32_16x16x32_bf16 v[36:39], v[168:171], v[184:187], v[36:39]
	v_mfma_f32_16x16x32_bf16 v[36:39], v[172:175], v[188:191], v[36:39]
	v_mfma_f32_16x16x32_bf16 v[52:55], v[168:171], v[176:179], v[52:55]
	v_mfma_f32_16x16x32_bf16 v[52:55], v[172:175], v[180:183], v[52:55]
	s_barrier
	s_setprio 0
	s_cbranch_scc0 .LBB0_2896
	s_cmpk_lt_u32 s22, 0x100
	s_cbranch_scc0 .LBB0_2899
	s_barrier

.LBB0_3116:
	v_add_u32_e32 v142, s26, v144
	ds_read_b128 v[146:149], v142
	ds_read_b128 v[150:153], v142 offset:1024
	ds_read_b128 v[154:157], v142 offset:2048
	ds_read_b128 v[158:161], v142 offset:3072
	v_add_u32_e32 v142, s40, v144
	ds_read_b128 v[162:165], v142
	ds_read_b128 v[166:169], v142 offset:1024
	ds_read_b128 v[170:173], v142 offset:2048
	ds_read_b128 v[174:177], v142 offset:3072
	s_add_u32 s18, s34, 0xfff80080
	s_addc_u32 s19, s35, -1
	s_cmp_eq_u32 s74, 28
	s_cselect_b32 s39, s13, s19
	s_cselect_b32 s38, s69, s18
	s_cselect_b32 s19, s11, s73
	s_cselect_b32 s18, s70, s71
	v_lshl_add_u64 v[142:143], s[34:35], 0, v[138:139]
	s_add_i32 m0, s43, 0xc000
	ds_read_b128 v[178:181], v145
	ds_read_b128 v[182:185], v145 offset:1024
	ds_read_b128 v[186:189], v145 offset:2048
	ds_read_b128 v[190:193], v145 offset:3072
	ds_read_b128 v[194:197], v145 offset:4096
	ds_read_b128 v[198:201], v145 offset:5120
	ds_read_b128 v[202:205], v145 offset:6144
	ds_read_b128 v[206:209], v145 offset:7168
	global_load_lds_dwordx4 v[142:143], off
	v_lshl_add_u64 v[142:143], s[34:35], 0, v[140:141]
	s_add_i32 m0, s43, 0xe000
	s_nop 0
	global_load_lds_dwordx4 v[142:143], off
	s_setprio 1
	s_waitcnt vmcnt(8)
	s_waitcnt lgkmcnt(0)
	s_barrier
	v_mfma_f32_16x16x32_bf16 v[128:131], v[146:149], v[178:181], v[128:131]
	v_mfma_f32_16x16x32_bf16 v[128:131], v[150:153], v[182:185], v[128:131]
	v_mfma_f32_16x16x32_bf16 v[112:115], v[146:149], v[186:189], v[112:115]
	v_mfma_f32_16x16x32_bf16 v[112:115], v[150:153], v[190:193], v[112:115]
	v_mfma_f32_16x16x32_bf16 v[96:99], v[146:149], v[194:197], v[96:99]
	v_mfma_f32_16x16x32_bf16 v[96:99], v[150:153], v[198:201], v[96:99]
	v_mfma_f32_16x16x32_bf16 v[80:83], v[146:149], v[202:205], v[80:83]
	v_mfma_f32_16x16x32_bf16 v[80:83], v[150:153], v[206:209], v[80:83]
	v_mfma_f32_16x16x32_bf16 v[72:75], v[154:157], v[202:205], v[72:75]
	v_mfma_f32_16x16x32_bf16 v[72:75], v[158:161], v[206:209], v[72:75]
	v_mfma_f32_16x16x32_bf16 v[88:91], v[154:157], v[194:197], v[88:91]
	v_mfma_f32_16x16x32_bf16 v[88:91], v[158:161], v[198:201], v[88:91]
	v_mfma_f32_16x16x32_bf16 v[104:107], v[154:157], v[186:189], v[104:107]
	v_mfma_f32_16x16x32_bf16 v[104:107], v[158:161], v[190:193], v[104:107]
	v_mfma_f32_16x16x32_bf16 v[120:123], v[154:157], v[178:181], v[120:123]
	v_mfma_f32_16x16x32_bf16 v[120:123], v[158:161], v[182:185], v[120:123]
	s_setprio 0
	s_setprio 1
	v_mfma_f32_16x16x32_bf16 v[124:127], v[162:165], v[178:181], v[124:127]
	v_mfma_f32_16x16x32_bf16 v[124:127], v[166:169], v[182:185], v[124:127]
	v_mfma_f32_16x16x32_bf16 v[108:111], v[162:165], v[186:189], v[108:111]
	v_mfma_f32_16x16x32_bf16 v[108:111], v[166:169], v[190:193], v[108:111]
	v_mfma_f32_16x16x32_bf16 v[92:95], v[162:165], v[194:197], v[92:95]
	v_mfma_f32_16x16x32_bf16 v[92:95], v[166:169], v[198:201], v[92:95]
	v_mfma_f32_16x16x32_bf16 v[76:79], v[162:165], v[202:205], v[76:79]
	v_mfma_f32_16x16x32_bf16 v[76:79], v[166:169], v[206:209], v[76:79]
	v_mfma_f32_16x16x32_bf16 v[68:71], v[170:173], v[202:205], v[68:71]
	v_mfma_f32_16x16x32_bf16 v[68:71], v[174:177], v[206:209], v[68:71]
	v_mfma_f32_16x16x32_bf16 v[84:87], v[170:173], v[194:197], v[84:87]
	v_mfma_f32_16x16x32_bf16 v[84:87], v[174:177], v[198:201], v[84:87]
	v_mfma_f32_16x16x32_bf16 v[100:103], v[170:173], v[186:189], v[100:103]
	v_mfma_f32_16x16x32_bf16 v[100:103], v[174:177], v[190:193], v[100:103]
	v_mfma_f32_16x16x32_bf16 v[116:119], v[170:173], v[178:181], v[116:119]
	v_mfma_f32_16x16x32_bf16 v[116:119], v[174:177], v[182:185], v[116:119]
	s_barrier
	s_setprio 0
	s_mov_b32 m0, s27
	v_lshl_add_u64 v[142:143], s[18:19], 0, v[2:3]
	s_add_u32 s76, s18, 0x80000
	ds_read_b128 v[178:181], v145 offset:16384
	ds_read_b128 v[182:185], v145 offset:17408
	ds_read_b128 v[186:189], v145 offset:18432
	ds_read_b128 v[190:193], v145 offset:19456
	ds_read_b128 v[194:197], v145 offset:20480
	ds_read_b128 v[198:201], v145 offset:21504
	ds_read_b128 v[202:205], v145 offset:22528
	ds_read_b128 v[206:209], v145 offset:23552
	global_load_lds_dwordx4 v[142:143], off
	v_lshl_add_u64 v[210:211], s[18:19], 0, v[132:133]
	s_mov_b32 m0, s37
	s_addc_u32 s77, s19, 0
	global_load_lds_dwordx4 v[210:211], off
	v_lshl_add_u64 v[212:213], s[76:77], 0, v[2:3]
	s_mov_b32 m0, s41
	v_lshl_add_u64 v[214:215], s[38:39], 0, v[134:135]
	global_load_lds_dwordx4 v[212:213], off
	v_lshl_add_u64 v[212:213], s[76:77], 0, v[132:133]
	s_mov_b32 m0, s42
	s_nop 0
	global_load_lds_dwordx4 v[212:213], off
	v_lshl_add_u64 v[212:213], s[38:39], 0, v[136:137]
	s_mov_b32 m0, s43
	s_nop 0
	global_load_lds_dwordx4 v[212:213], off
	s_mov_b32 m0, s44
	s_nop 0
	global_load_lds_dwordx4 v[214:215], off
	s_setprio 1
	s_waitcnt vmcnt(8)
	s_waitcnt lgkmcnt(0)
	s_barrier
	v_mfma_f32_16x16x32_bf16 v[64:67], v[146:149], v[178:181], v[64:67]
	v_mfma_f32_16x16x32_bf16 v[64:67], v[150:153], v[182:185], v[64:67]
	v_mfma_f32_16x16x32_bf16 v[48:51], v[146:149], v[186:189], v[48:51]
	v_mfma_f32_16x16x32_bf16 v[48:51], v[150:153], v[190:193], v[48:51]
	v_mfma_f32_16x16x32_bf16 v[32:35], v[146:149], v[194:197], v[32:35]
	v_mfma_f32_16x16x32_bf16 v[32:35], v[150:153], v[198:201], v[32:35]
	v_mfma_f32_16x16x32_bf16 v[16:19], v[146:149], v[202:205], v[16:19]
	v_mfma_f32_16x16x32_bf16 v[16:19], v[150:153], v[206:209], v[16:19]
	v_mfma_f32_16x16x32_bf16 v[8:11], v[154:157], v[202:205], v[8:11]
	v_mfma_f32_16x16x32_bf16 v[8:11], v[158:161], v[206:209], v[8:11]
	v_mfma_f32_16x16x32_bf16 v[24:27], v[154:157], v[194:197], v[24:27]
	v_mfma_f32_16x16x32_bf16 v[24:27], v[158:161], v[198:201], v[24:27]
	v_mfma_f32_16x16x32_bf16 v[40:43], v[154:157], v[186:189], v[40:43]
	v_mfma_f32_16x16x32_bf16 v[40:43], v[158:161], v[190:193], v[40:43]
	v_mfma_f32_16x16x32_bf16 v[56:59], v[154:157], v[178:181], v[56:59]
	v_mfma_f32_16x16x32_bf16 v[56:59], v[158:161], v[182:185], v[56:59]
	s_setprio 0
	s_setprio 1
	v_mfma_f32_16x16x32_bf16 v[60:63], v[162:165], v[178:181], v[60:63]
	v_mfma_f32_16x16x32_bf16 v[60:63], v[166:169], v[182:185], v[60:63]
	v_mfma_f32_16x16x32_bf16 v[44:47], v[162:165], v[186:189], v[44:47]
	v_mfma_f32_16x16x32_bf16 v[44:47], v[166:169], v[190:193], v[44:47]
	v_mfma_f32_16x16x32_bf16 v[28:31], v[162:165], v[194:197], v[28:31]
	v_mfma_f32_16x16x32_bf16 v[28:31], v[166:169], v[198:201], v[28:31]
	v_mfma_f32_16x16x32_bf16 v[12:15], v[162:165], v[202:205], v[12:15]
	v_mfma_f32_16x16x32_bf16 v[12:15], v[166:169], v[206:209], v[12:15]
	v_mfma_f32_16x16x32_bf16 v[4:7], v[170:173], v[202:205], v[4:7]
	v_mfma_f32_16x16x32_bf16 v[4:7], v[174:177], v[206:209], v[4:7]
	v_mfma_f32_16x16x32_bf16 v[20:23], v[170:173], v[194:197], v[20:23]
	v_mfma_f32_16x16x32_bf16 v[20:23], v[174:177], v[198:201], v[20:23]
	v_mfma_f32_16x16x32_bf16 v[36:39], v[170:173], v[186:189], v[36:39]
	v_mfma_f32_16x16x32_bf16 v[36:39], v[174:177], v[190:193], v[36:39]
	v_mfma_f32_16x16x32_bf16 v[52:55], v[170:173], v[178:181], v[52:55]
	v_mfma_f32_16x16x32_bf16 v[52:55], v[174:177], v[182:185], v[52:55]
	s_barrier
	s_setprio 0
	v_add_u32_e32 v158, s49, v144
	v_add_u32_e32 v174, s56, v144
	ds_read_b128 v[146:149], v158
	ds_read_b128 v[150:153], v158 offset:1024
	ds_read_b128 v[154:157], v158 offset:2048
	ds_read_b128 v[158:161], v158 offset:3072
	ds_read_b128 v[162:165], v174
	ds_read_b128 v[166:169], v174 offset:1024
	ds_read_b128 v[170:173], v174 offset:2048
	ds_read_b128 v[174:177], v174 offset:3072
	s_add_u32 s38, s38, 0x80000
	s_addc_u32 s39, s39, 0
	s_mov_b32 m0, s45
	v_lshl_add_u64 v[216:217], s[38:39], 0, v[136:137]
	ds_read_b128 v[178:181], v145 offset:32768
	ds_read_b128 v[182:185], v145 offset:33792
	ds_read_b128 v[186:189], v145 offset:34816
	ds_read_b128 v[190:193], v145 offset:35840
	ds_read_b128 v[194:197], v145 offset:36864
	ds_read_b128 v[198:201], v145 offset:37888
	ds_read_b128 v[202:205], v145 offset:38912
	ds_read_b128 v[206:209], v145 offset:39936
	global_load_lds_dwordx4 v[216:217], off
	v_lshl_add_u64 v[216:217], s[38:39], 0, v[134:135]
	s_mov_b32 m0, s46
	s_nop 0
	global_load_lds_dwordx4 v[216:217], off
	s_setprio 1
	s_waitcnt vmcnt(8)
	s_waitcnt lgkmcnt(0)
	s_barrier
	v_mfma_f32_16x16x32_bf16 v[128:131], v[146:149], v[178:181], v[128:131]
	v_mfma_f32_16x16x32_bf16 v[128:131], v[150:153], v[182:185], v[128:131]
	v_mfma_f32_16x16x32_bf16 v[112:115], v[146:149], v[186:189], v[112:115]
	v_mfma_f32_16x16x32_bf16 v[112:115], v[150:153], v[190:193], v[112:115]
	v_mfma_f32_16x16x32_bf16 v[96:99], v[146:149], v[194:197], v[96:99]
	v_mfma_f32_16x16x32_bf16 v[96:99], v[150:153], v[198:201], v[96:99]
	v_mfma_f32_16x16x32_bf16 v[80:83], v[146:149], v[202:205], v[80:83]
	v_mfma_f32_16x16x32_bf16 v[80:83], v[150:153], v[206:209], v[80:83]
	v_mfma_f32_16x16x32_bf16 v[72:75], v[154:157], v[202:205], v[72:75]
	v_mfma_f32_16x16x32_bf16 v[72:75], v[158:161], v[206:209], v[72:75]
	v_mfma_f32_16x16x32_bf16 v[88:91], v[154:157], v[194:197], v[88:91]
	v_mfma_f32_16x16x32_bf16 v[88:91], v[158:161], v[198:201], v[88:91]
	v_mfma_f32_16x16x32_bf16 v[104:107], v[154:157], v[186:189], v[104:107]
	v_mfma_f32_16x16x32_bf16 v[104:107], v[158:161], v[190:193], v[104:107]
	v_mfma_f32_16x16x32_bf16 v[120:123], v[154:157], v[178:181], v[120:123]
	v_mfma_f32_16x16x32_bf16 v[120:123], v[158:161], v[182:185], v[120:123]
	s_setprio 0
	s_setprio 1
	v_mfma_f32_16x16x32_bf16 v[124:127], v[162:165], v[178:181], v[124:127]
	v_mfma_f32_16x16x32_bf16 v[124:127], v[166:169], v[182:185], v[124:127]
	v_mfma_f32_16x16x32_bf16 v[108:111], v[162:165], v[186:189], v[108:111]
	v_mfma_f32_16x16x32_bf16 v[108:111], v[166:169], v[190:193], v[108:111]
	v_mfma_f32_16x16x32_bf16 v[92:95], v[162:165], v[194:197], v[92:95]
	v_mfma_f32_16x16x32_bf16 v[92:95], v[166:169], v[198:201], v[92:95]
	v_mfma_f32_16x16x32_bf16 v[76:79], v[162:165], v[202:205], v[76:79]
	v_mfma_f32_16x16x32_bf16 v[76:79], v[166:169], v[206:209], v[76:79]
	v_mfma_f32_16x16x32_bf16 v[68:71], v[170:173], v[202:205], v[68:71]
	v_mfma_f32_16x16x32_bf16 v[68:71], v[174:177], v[206:209], v[68:71]
	v_mfma_f32_16x16x32_bf16 v[84:87], v[170:173], v[194:197], v[84:87]
	v_mfma_f32_16x16x32_bf16 v[84:87], v[174:177], v[198:201], v[84:87]
	v_mfma_f32_16x16x32_bf16 v[100:103], v[170:173], v[186:189], v[100:103]
	v_mfma_f32_16x16x32_bf16 v[100:103], v[174:177], v[190:193], v[100:103]
	v_mfma_f32_16x16x32_bf16 v[116:119], v[170:173], v[178:181], v[116:119]
	v_mfma_f32_16x16x32_bf16 v[116:119], v[174:177], v[182:185], v[116:119]
	s_barrier
	s_setprio 0
	s_mov_b32 m0, s50
	v_lshl_add_u64 v[142:143], v[142:143], 0, s[64:65]
	s_add_u32 s18, s18, 0x80080
	ds_read_b128 v[178:181], v145 offset:49152
	ds_read_b128 v[182:185], v145 offset:50176
	ds_read_b128 v[186:189], v145 offset:51200
	ds_read_b128 v[190:193], v145 offset:52224
	ds_read_b128 v[194:197], v145 offset:53248
	ds_read_b128 v[198:201], v145 offset:54272
	ds_read_b128 v[202:205], v145 offset:55296
	ds_read_b128 v[206:209], v145 offset:56320
	global_load_lds_dwordx4 v[142:143], off
	v_lshl_add_u64 v[142:143], v[210:211], 0, s[64:65]
	s_mov_b32 m0, s51
	s_addc_u32 s19, s19, 0
	global_load_lds_dwordx4 v[142:143], off
	v_lshl_add_u64 v[142:143], s[18:19], 0, v[2:3]
	s_mov_b32 m0, s57
	s_nop 0
	global_load_lds_dwordx4 v[142:143], off
	v_lshl_add_u64 v[142:143], s[18:19], 0, v[132:133]
	s_mov_b32 m0, s58
	s_nop 0
	global_load_lds_dwordx4 v[142:143], off
	v_lshl_add_u64 v[142:143], v[212:213], 0, s[64:65]
	s_mov_b32 m0, s52
	s_nop 0
	global_load_lds_dwordx4 v[142:143], off
	v_lshl_add_u64 v[142:143], v[214:215], 0, s[64:65]
	s_mov_b32 m0, s53
	s_nop 0
	global_load_lds_dwordx4 v[142:143], off
	s_setprio 1
	s_waitcnt vmcnt(8)
	s_waitcnt lgkmcnt(0)
	s_barrier
	v_mfma_f32_16x16x32_bf16 v[64:67], v[146:149], v[178:181], v[64:67]
	v_mfma_f32_16x16x32_bf16 v[64:67], v[150:153], v[182:185], v[64:67]
	v_mfma_f32_16x16x32_bf16 v[48:51], v[146:149], v[186:189], v[48:51]
	v_mfma_f32_16x16x32_bf16 v[48:51], v[150:153], v[190:193], v[48:51]
	v_mfma_f32_16x16x32_bf16 v[32:35], v[146:149], v[194:197], v[32:35]
	v_mfma_f32_16x16x32_bf16 v[32:35], v[150:153], v[198:201], v[32:35]
	v_mfma_f32_16x16x32_bf16 v[16:19], v[146:149], v[202:205], v[16:19]
	v_mfma_f32_16x16x32_bf16 v[16:19], v[150:153], v[206:209], v[16:19]
	v_mfma_f32_16x16x32_bf16 v[8:11], v[154:157], v[202:205], v[8:11]
	v_mfma_f32_16x16x32_bf16 v[8:11], v[158:161], v[206:209], v[8:11]
	v_mfma_f32_16x16x32_bf16 v[24:27], v[154:157], v[194:197], v[24:27]
	v_mfma_f32_16x16x32_bf16 v[24:27], v[158:161], v[198:201], v[24:27]
	v_mfma_f32_16x16x32_bf16 v[40:43], v[154:157], v[186:189], v[40:43]
	v_mfma_f32_16x16x32_bf16 v[40:43], v[158:161], v[190:193], v[40:43]
	v_mfma_f32_16x16x32_bf16 v[56:59], v[154:157], v[178:181], v[56:59]
	v_mfma_f32_16x16x32_bf16 v[56:59], v[158:161], v[182:185], v[56:59]
	s_setprio 0
	s_setprio 1
	v_mfma_f32_16x16x32_bf16 v[60:63], v[162:165], v[178:181], v[60:63]
	v_mfma_f32_16x16x32_bf16 v[60:63], v[166:169], v[182:185], v[60:63]
	v_mfma_f32_16x16x32_bf16 v[44:47], v[162:165], v[186:189], v[44:47]
	v_mfma_f32_16x16x32_bf16 v[44:47], v[166:169], v[190:193], v[44:47]
	v_mfma_f32_16x16x32_bf16 v[28:31], v[162:165], v[194:197], v[28:31]
	v_mfma_f32_16x16x32_bf16 v[28:31], v[166:169], v[198:201], v[28:31]
	v_mfma_f32_16x16x32_bf16 v[12:15], v[162:165], v[202:205], v[12:15]
	v_mfma_f32_16x16x32_bf16 v[12:15], v[166:169], v[206:209], v[12:15]
	s_add_i32 s74, s74, 2
	v_mfma_f32_16x16x32_bf16 v[4:7], v[170:173], v[202:205], v[4:7]
	v_mfma_f32_16x16x32_bf16 v[4:7], v[174:177], v[206:209], v[4:7]
	s_add_u32 s34, s34, 0x100
	s_addc_u32 s35, s35, 0
	v_mfma_f32_16x16x32_bf16 v[20:23], v[170:173], v[194:197], v[20:23]
	v_mfma_f32_16x16x32_bf16 v[20:23], v[174:177], v[198:201], v[20:23]
	s_add_u32 s71, s71, 0x100
	s_addc_u32 s73, s73, 0
	v_mfma_f32_16x16x32_bf16 v[36:39], v[170:173], v[186:189], v[36:39]
	v_mfma_f32_16x16x32_bf16 v[36:39], v[174:177], v[190:193], v[36:39]
	s_cmp_gt_u32 s74, 29
	v_mfma_f32_16x16x32_bf16 v[52:55], v[170:173], v[178:181], v[52:55]
	v_mfma_f32_16x16x32_bf16 v[52:55], v[174:177], v[182:185], v[52:55]
	s_barrier
	s_setprio 0
	s_cbranch_scc0 .LBB0_3116
	s_and_b64 vcc, exec, s[8:9]
	s_cbranch_vccz .LBB0_3119
	s_barrier

.LBB0_3195:
	v_add_u32_e32 v144, s26, v249
	v_add_u32_e32 v160, s38, v249
	ds_read_b128 v[132:135], v144
	ds_read_b128 v[136:139], v144 offset:1024
	ds_read_b128 v[140:143], v144 offset:2048
	ds_read_b128 v[144:147], v144 offset:3072
	ds_read_b128 v[148:151], v160
	ds_read_b128 v[152:155], v160 offset:1024
	ds_read_b128 v[156:159], v160 offset:2048
	ds_read_b128 v[160:163], v160 offset:3072
	s_add_u32 s24, s14, 0x100
	s_addc_u32 s25, s15, 0
	s_cmpk_eq_i32 s74, 0x54
	s_cselect_b32 s35, s5, s25
	s_cselect_b32 s34, s4, s24
	s_cselect_b32 s19, s13, s73
	s_cselect_b32 s18, s12, s71
	v_lshl_add_u64 v[196:197], s[14:15], 0, v[222:223]
	s_add_i32 m0, s41, 0xc000
	ds_read_b128 v[164:167], v250
	ds_read_b128 v[168:171], v250 offset:1024
	ds_read_b128 v[172:175], v250 offset:2048
	ds_read_b128 v[176:179], v250 offset:3072
	ds_read_b128 v[180:183], v250 offset:4096
	ds_read_b128 v[184:187], v250 offset:5120
	ds_read_b128 v[188:191], v250 offset:6144
	ds_read_b128 v[192:195], v250 offset:7168
	global_load_lds_dwordx4 v[196:197], off
	v_lshl_add_u64 v[196:197], s[14:15], 0, v[224:225]
	s_add_i32 m0, s41, 0xe000
	s_nop 0
	global_load_lds_dwordx4 v[196:197], off
	s_setprio 1
	s_waitcnt vmcnt(8)
	s_waitcnt lgkmcnt(0)
	s_barrier
	v_mfma_f32_16x16x32_bf16 v[128:131], v[132:135], v[164:167], v[128:131]
	v_mfma_f32_16x16x32_bf16 v[128:131], v[136:139], v[168:171], v[128:131]
	v_mfma_f32_16x16x32_bf16 v[112:115], v[132:135], v[172:175], v[112:115]
	v_mfma_f32_16x16x32_bf16 v[112:115], v[136:139], v[176:179], v[112:115]
	v_mfma_f32_16x16x32_bf16 v[96:99], v[132:135], v[180:183], v[96:99]
	v_mfma_f32_16x16x32_bf16 v[96:99], v[136:139], v[184:187], v[96:99]
	v_mfma_f32_16x16x32_bf16 v[80:83], v[132:135], v[188:191], v[80:83]
	v_mfma_f32_16x16x32_bf16 v[80:83], v[136:139], v[192:195], v[80:83]
	v_mfma_f32_16x16x32_bf16 v[76:79], v[140:143], v[188:191], v[76:79]
	v_mfma_f32_16x16x32_bf16 v[76:79], v[144:147], v[192:195], v[76:79]
	v_mfma_f32_16x16x32_bf16 v[92:95], v[140:143], v[180:183], v[92:95]
	v_mfma_f32_16x16x32_bf16 v[92:95], v[144:147], v[184:187], v[92:95]
	v_mfma_f32_16x16x32_bf16 v[108:111], v[140:143], v[172:175], v[108:111]
	v_mfma_f32_16x16x32_bf16 v[108:111], v[144:147], v[176:179], v[108:111]
	v_mfma_f32_16x16x32_bf16 v[124:127], v[140:143], v[164:167], v[124:127]
	v_mfma_f32_16x16x32_bf16 v[124:127], v[144:147], v[168:171], v[124:127]
	s_setprio 0
	s_setprio 1
	v_mfma_f32_16x16x32_bf16 v[120:123], v[148:151], v[164:167], v[120:123]
	v_mfma_f32_16x16x32_bf16 v[120:123], v[152:155], v[168:171], v[120:123]
	v_mfma_f32_16x16x32_bf16 v[104:107], v[148:151], v[172:175], v[104:107]
	v_mfma_f32_16x16x32_bf16 v[104:107], v[152:155], v[176:179], v[104:107]
	v_mfma_f32_16x16x32_bf16 v[88:91], v[148:151], v[180:183], v[88:91]
	v_mfma_f32_16x16x32_bf16 v[88:91], v[152:155], v[184:187], v[88:91]
	v_mfma_f32_16x16x32_bf16 v[72:75], v[148:151], v[188:191], v[72:75]
	v_mfma_f32_16x16x32_bf16 v[72:75], v[152:155], v[192:195], v[72:75]
	v_mfma_f32_16x16x32_bf16 v[68:71], v[156:159], v[188:191], v[68:71]
	v_mfma_f32_16x16x32_bf16 v[68:71], v[160:163], v[192:195], v[68:71]
	v_mfma_f32_16x16x32_bf16 v[84:87], v[156:159], v[180:183], v[84:87]
	v_mfma_f32_16x16x32_bf16 v[84:87], v[160:163], v[184:187], v[84:87]
	v_mfma_f32_16x16x32_bf16 v[100:103], v[156:159], v[172:175], v[100:103]
	v_mfma_f32_16x16x32_bf16 v[100:103], v[160:163], v[176:179], v[100:103]
	v_mfma_f32_16x16x32_bf16 v[116:119], v[156:159], v[164:167], v[116:119]
	v_mfma_f32_16x16x32_bf16 v[116:119], v[160:163], v[168:171], v[116:119]
	s_barrier
	s_setprio 0
	s_mov_b32 m0, s27
	v_lshl_add_u64 v[196:197], s[18:19], 0, v[2:3]
	s_add_u32 s14, s18, 0x160000
	ds_read_b128 v[164:167], v250 offset:16384
	ds_read_b128 v[168:171], v250 offset:17408
	ds_read_b128 v[172:175], v250 offset:18432
	ds_read_b128 v[176:179], v250 offset:19456
	ds_read_b128 v[180:183], v250 offset:20480
	ds_read_b128 v[184:187], v250 offset:21504
	ds_read_b128 v[188:191], v250 offset:22528
	ds_read_b128 v[192:195], v250 offset:23552
	global_load_lds_dwordx4 v[196:197], off
	v_lshl_add_u64 v[198:199], s[18:19], 0, v[216:217]
	s_mov_b32 m0, s37
	s_addc_u32 s15, s19, 0
	global_load_lds_dwordx4 v[198:199], off
	v_lshl_add_u64 v[200:201], s[14:15], 0, v[2:3]
	s_mov_b32 m0, s39
	v_lshl_add_u64 v[202:203], s[34:35], 0, v[218:219]
	global_load_lds_dwordx4 v[200:201], off
	v_lshl_add_u64 v[200:201], s[14:15], 0, v[216:217]
	s_mov_b32 m0, s40
	s_nop 0
	global_load_lds_dwordx4 v[200:201], off
	v_lshl_add_u64 v[200:201], s[34:35], 0, v[220:221]
	s_mov_b32 m0, s41
	s_nop 0
	global_load_lds_dwordx4 v[200:201], off
	s_mov_b32 m0, s42
	s_nop 0
	global_load_lds_dwordx4 v[202:203], off
	s_setprio 1
	s_waitcnt vmcnt(8)
	s_waitcnt lgkmcnt(0)
	s_barrier
	v_mfma_f32_16x16x32_bf16 v[64:67], v[132:135], v[164:167], v[64:67]
	v_mfma_f32_16x16x32_bf16 v[64:67], v[136:139], v[168:171], v[64:67]
	v_mfma_f32_16x16x32_bf16 v[48:51], v[132:135], v[172:175], v[48:51]
	v_mfma_f32_16x16x32_bf16 v[48:51], v[136:139], v[176:179], v[48:51]
	v_mfma_f32_16x16x32_bf16 v[32:35], v[132:135], v[180:183], v[32:35]
	v_mfma_f32_16x16x32_bf16 v[32:35], v[136:139], v[184:187], v[32:35]
	v_mfma_f32_16x16x32_bf16 v[16:19], v[132:135], v[188:191], v[16:19]
	v_mfma_f32_16x16x32_bf16 v[16:19], v[136:139], v[192:195], v[16:19]
	v_mfma_f32_16x16x32_bf16 v[12:15], v[140:143], v[188:191], v[12:15]
	v_mfma_f32_16x16x32_bf16 v[12:15], v[144:147], v[192:195], v[12:15]
	v_mfma_f32_16x16x32_bf16 v[28:31], v[140:143], v[180:183], v[28:31]
	v_mfma_f32_16x16x32_bf16 v[28:31], v[144:147], v[184:187], v[28:31]
	v_mfma_f32_16x16x32_bf16 v[44:47], v[140:143], v[172:175], v[44:47]
	v_mfma_f32_16x16x32_bf16 v[44:47], v[144:147], v[176:179], v[44:47]
	v_mfma_f32_16x16x32_bf16 v[60:63], v[140:143], v[164:167], v[60:63]
	v_mfma_f32_16x16x32_bf16 v[60:63], v[144:147], v[168:171], v[60:63]
	s_setprio 0
	s_setprio 1
	v_mfma_f32_16x16x32_bf16 v[56:59], v[148:151], v[164:167], v[56:59]
	v_mfma_f32_16x16x32_bf16 v[56:59], v[152:155], v[168:171], v[56:59]
	v_mfma_f32_16x16x32_bf16 v[40:43], v[148:151], v[172:175], v[40:43]
	v_mfma_f32_16x16x32_bf16 v[40:43], v[152:155], v[176:179], v[40:43]
	v_mfma_f32_16x16x32_bf16 v[24:27], v[148:151], v[180:183], v[24:27]
	v_mfma_f32_16x16x32_bf16 v[24:27], v[152:155], v[184:187], v[24:27]
	v_mfma_f32_16x16x32_bf16 v[8:11], v[148:151], v[188:191], v[8:11]
	v_mfma_f32_16x16x32_bf16 v[8:11], v[152:155], v[192:195], v[8:11]
	v_mfma_f32_16x16x32_bf16 v[4:7], v[156:159], v[188:191], v[4:7]
	v_mfma_f32_16x16x32_bf16 v[4:7], v[160:163], v[192:195], v[4:7]
	v_mfma_f32_16x16x32_bf16 v[20:23], v[156:159], v[180:183], v[20:23]
	v_mfma_f32_16x16x32_bf16 v[20:23], v[160:163], v[184:187], v[20:23]
	v_mfma_f32_16x16x32_bf16 v[36:39], v[156:159], v[172:175], v[36:39]
	v_mfma_f32_16x16x32_bf16 v[36:39], v[160:163], v[176:179], v[36:39]
	v_mfma_f32_16x16x32_bf16 v[52:55], v[156:159], v[164:167], v[52:55]
	v_mfma_f32_16x16x32_bf16 v[52:55], v[160:163], v[168:171], v[52:55]
	s_barrier
	s_setprio 0
	v_add_u32_e32 v144, s49, v249
	v_add_u32_e32 v160, s56, v249
	ds_read_b128 v[132:135], v144
	ds_read_b128 v[136:139], v144 offset:1024
	ds_read_b128 v[140:143], v144 offset:2048
	ds_read_b128 v[144:147], v144 offset:3072
	ds_read_b128 v[148:151], v160
	ds_read_b128 v[152:155], v160 offset:1024
	ds_read_b128 v[156:159], v160 offset:2048
	ds_read_b128 v[160:163], v160 offset:3072
	s_add_u32 s14, s34, 0x160000
	s_addc_u32 s15, s35, 0
	s_mov_b32 m0, s43
	v_lshl_add_u64 v[204:205], s[14:15], 0, v[220:221]
	ds_read_b128 v[164:167], v250 offset:32768
	ds_read_b128 v[168:171], v250 offset:33792
	ds_read_b128 v[172:175], v250 offset:34816
	ds_read_b128 v[176:179], v250 offset:35840
	ds_read_b128 v[180:183], v250 offset:36864
	ds_read_b128 v[184:187], v250 offset:37888
	ds_read_b128 v[188:191], v250 offset:38912
	ds_read_b128 v[192:195], v250 offset:39936
	global_load_lds_dwordx4 v[204:205], off
	v_lshl_add_u64 v[204:205], s[14:15], 0, v[218:219]
	s_mov_b32 m0, s44
	s_nop 0
	global_load_lds_dwordx4 v[204:205], off
	s_setprio 1
	s_waitcnt vmcnt(8)
	s_waitcnt lgkmcnt(0)
	s_barrier
	v_mfma_f32_16x16x32_bf16 v[128:131], v[132:135], v[164:167], v[128:131]
	v_mfma_f32_16x16x32_bf16 v[128:131], v[136:139], v[168:171], v[128:131]
	v_mfma_f32_16x16x32_bf16 v[112:115], v[132:135], v[172:175], v[112:115]
	v_mfma_f32_16x16x32_bf16 v[112:115], v[136:139], v[176:179], v[112:115]
	v_mfma_f32_16x16x32_bf16 v[96:99], v[132:135], v[180:183], v[96:99]
	v_mfma_f32_16x16x32_bf16 v[96:99], v[136:139], v[184:187], v[96:99]
	v_mfma_f32_16x16x32_bf16 v[80:83], v[132:135], v[188:191], v[80:83]
	v_mfma_f32_16x16x32_bf16 v[80:83], v[136:139], v[192:195], v[80:83]
	v_mfma_f32_16x16x32_bf16 v[76:79], v[140:143], v[188:191], v[76:79]
	v_mfma_f32_16x16x32_bf16 v[76:79], v[144:147], v[192:195], v[76:79]
	v_mfma_f32_16x16x32_bf16 v[92:95], v[140:143], v[180:183], v[92:95]
	v_mfma_f32_16x16x32_bf16 v[92:95], v[144:147], v[184:187], v[92:95]
	v_mfma_f32_16x16x32_bf16 v[108:111], v[140:143], v[172:175], v[108:111]
	v_mfma_f32_16x16x32_bf16 v[108:111], v[144:147], v[176:179], v[108:111]
	v_mfma_f32_16x16x32_bf16 v[124:127], v[140:143], v[164:167], v[124:127]
	v_mfma_f32_16x16x32_bf16 v[124:127], v[144:147], v[168:171], v[124:127]
	s_setprio 0
	s_setprio 1
	v_mfma_f32_16x16x32_bf16 v[120:123], v[148:151], v[164:167], v[120:123]
	v_mfma_f32_16x16x32_bf16 v[120:123], v[152:155], v[168:171], v[120:123]
	v_mfma_f32_16x16x32_bf16 v[104:107], v[148:151], v[172:175], v[104:107]
	v_mfma_f32_16x16x32_bf16 v[104:107], v[152:155], v[176:179], v[104:107]
	v_mfma_f32_16x16x32_bf16 v[88:91], v[148:151], v[180:183], v[88:91]
	v_mfma_f32_16x16x32_bf16 v[88:91], v[152:155], v[184:187], v[88:91]
	v_mfma_f32_16x16x32_bf16 v[72:75], v[148:151], v[188:191], v[72:75]
	v_mfma_f32_16x16x32_bf16 v[72:75], v[152:155], v[192:195], v[72:75]
	v_mfma_f32_16x16x32_bf16 v[68:71], v[156:159], v[188:191], v[68:71]
	v_mfma_f32_16x16x32_bf16 v[68:71], v[160:163], v[192:195], v[68:71]
	v_mfma_f32_16x16x32_bf16 v[84:87], v[156:159], v[180:183], v[84:87]
	v_mfma_f32_16x16x32_bf16 v[84:87], v[160:163], v[184:187], v[84:87]
	v_mfma_f32_16x16x32_bf16 v[100:103], v[156:159], v[172:175], v[100:103]
	v_mfma_f32_16x16x32_bf16 v[100:103], v[160:163], v[176:179], v[100:103]
	v_mfma_f32_16x16x32_bf16 v[116:119], v[156:159], v[164:167], v[116:119]
	v_mfma_f32_16x16x32_bf16 v[116:119], v[160:163], v[168:171], v[116:119]
	s_barrier
	s_setprio 0
	s_mov_b32 m0, s50
	v_lshl_add_u64 v[196:197], v[196:197], 0, s[64:65]
	s_add_u32 s14, s18, 0x160080
	ds_read_b128 v[164:167], v250 offset:49152
	ds_read_b128 v[168:171], v250 offset:50176
	ds_read_b128 v[172:175], v250 offset:51200
	ds_read_b128 v[176:179], v250 offset:52224
	ds_read_b128 v[180:183], v250 offset:53248
	ds_read_b128 v[184:187], v250 offset:54272
	ds_read_b128 v[188:191], v250 offset:55296
	ds_read_b128 v[192:195], v250 offset:56320
	global_load_lds_dwordx4 v[196:197], off
	v_lshl_add_u64 v[196:197], v[198:199], 0, s[64:65]
	s_mov_b32 m0, s51
	s_addc_u32 s15, s19, 0
	global_load_lds_dwordx4 v[196:197], off
	v_lshl_add_u64 v[196:197], s[14:15], 0, v[2:3]
	s_mov_b32 m0, s57
	s_nop 0
	global_load_lds_dwordx4 v[196:197], off
	v_lshl_add_u64 v[196:197], s[14:15], 0, v[216:217]
	s_mov_b32 m0, s58
	s_nop 0
	global_load_lds_dwordx4 v[196:197], off
	v_lshl_add_u64 v[196:197], v[200:201], 0, s[64:65]
	s_mov_b32 m0, s52
	s_nop 0
	global_load_lds_dwordx4 v[196:197], off
	v_lshl_add_u64 v[196:197], v[202:203], 0, s[64:65]
	s_mov_b32 m0, s53
	s_nop 0
	global_load_lds_dwordx4 v[196:197], off
	s_setprio 1
	s_waitcnt vmcnt(8)
	s_waitcnt lgkmcnt(0)
	s_barrier
	v_mfma_f32_16x16x32_bf16 v[64:67], v[132:135], v[164:167], v[64:67]
	v_mfma_f32_16x16x32_bf16 v[64:67], v[136:139], v[168:171], v[64:67]
	v_mfma_f32_16x16x32_bf16 v[48:51], v[132:135], v[172:175], v[48:51]
	v_mfma_f32_16x16x32_bf16 v[48:51], v[136:139], v[176:179], v[48:51]
	v_mfma_f32_16x16x32_bf16 v[32:35], v[132:135], v[180:183], v[32:35]
	v_mfma_f32_16x16x32_bf16 v[32:35], v[136:139], v[184:187], v[32:35]
	v_mfma_f32_16x16x32_bf16 v[16:19], v[132:135], v[188:191], v[16:19]
	v_mfma_f32_16x16x32_bf16 v[16:19], v[136:139], v[192:195], v[16:19]
	v_mfma_f32_16x16x32_bf16 v[12:15], v[140:143], v[188:191], v[12:15]
	v_mfma_f32_16x16x32_bf16 v[12:15], v[144:147], v[192:195], v[12:15]
	v_mfma_f32_16x16x32_bf16 v[28:31], v[140:143], v[180:183], v[28:31]
	v_mfma_f32_16x16x32_bf16 v[28:31], v[144:147], v[184:187], v[28:31]
	v_mfma_f32_16x16x32_bf16 v[44:47], v[140:143], v[172:175], v[44:47]
	v_mfma_f32_16x16x32_bf16 v[44:47], v[144:147], v[176:179], v[44:47]
	v_mfma_f32_16x16x32_bf16 v[60:63], v[140:143], v[164:167], v[60:63]
	v_mfma_f32_16x16x32_bf16 v[60:63], v[144:147], v[168:171], v[60:63]
	s_setprio 0
	s_setprio 1
	v_mfma_f32_16x16x32_bf16 v[56:59], v[148:151], v[164:167], v[56:59]
	v_mfma_f32_16x16x32_bf16 v[56:59], v[152:155], v[168:171], v[56:59]
	v_mfma_f32_16x16x32_bf16 v[40:43], v[148:151], v[172:175], v[40:43]
	v_mfma_f32_16x16x32_bf16 v[40:43], v[152:155], v[176:179], v[40:43]
	v_mfma_f32_16x16x32_bf16 v[24:27], v[148:151], v[180:183], v[24:27]
	v_mfma_f32_16x16x32_bf16 v[24:27], v[152:155], v[184:187], v[24:27]
	v_mfma_f32_16x16x32_bf16 v[8:11], v[148:151], v[188:191], v[8:11]
	v_mfma_f32_16x16x32_bf16 v[8:11], v[152:155], v[192:195], v[8:11]
	s_add_i32 s74, s74, 2
	v_mfma_f32_16x16x32_bf16 v[4:7], v[156:159], v[188:191], v[4:7]
	v_mfma_f32_16x16x32_bf16 v[4:7], v[160:163], v[192:195], v[4:7]
	s_add_u32 s71, s71, 0x100
	s_addc_u32 s73, s73, 0
	v_mfma_f32_16x16x32_bf16 v[20:23], v[156:159], v[180:183], v[20:23]
	v_mfma_f32_16x16x32_bf16 v[20:23], v[160:163], v[184:187], v[20:23]
	s_cmpk_gt_u32 s74, 0x55
	v_mfma_f32_16x16x32_bf16 v[36:39], v[156:159], v[172:175], v[36:39]
	v_mfma_f32_16x16x32_bf16 v[36:39], v[160:163], v[176:179], v[36:39]
	v_mfma_f32_16x16x32_bf16 v[52:55], v[156:159], v[164:167], v[52:55]
	v_mfma_f32_16x16x32_bf16 v[52:55], v[160:163], v[168:171], v[52:55]
	s_barrier
	s_setprio 0
	s_mov_b64 s[14:15], s[24:25]
	s_cbranch_scc0 .LBB0_3195
	s_and_b64 vcc, exec, s[10:11]
	s_cbranch_vccz .LBB0_3198
	s_barrier
